# GEMM phases: in-loop LDS-DMA loads use the SGPR-base + 32-bit VGPR offset form (drops one 64-bit VALU add per load)
# speedup vs baseline: 1.0065x; 1.0065x over previous
.LBB0_156:
	s_add_u32 s69, s76, 0x2c00800
	s_addc_u32 s70, s77, 0
	s_add_u32 s71, s76, 0x100800
	s_mov_b64 s[14:15], 0x80
	s_addc_u32 s72, s77, 0
	s_add_i32 m0, s29, 0x18000
	v_lshl_add_u64 v[6:7], v[6:7], 0, s[14:15]
	s_and_b32 s16, s1, 3
	s_waitcnt vmcnt(2)
	s_barrier
	global_load_lds_dwordx4 v[6:7], off
	v_lshl_add_u64 v[4:5], v[4:5], 0, s[14:15]
	s_add_i32 m0, s29, 0x1a000
	s_add_i32 s73, s29, 0x8000
	s_lshl_b32 s1, s0, 13
	s_lshl_b32 s18, s16, 12
	global_load_lds_dwordx4 v[4:5], off
	v_lshl_add_u64 v[0:1], v[0:1], 0, s[14:15]
	s_mov_b32 m0, s73
	s_add_i32 s78, s29, 0xa000
	global_load_lds_dwordx4 v[0:1], off
	v_lshl_add_u64 v[0:1], v[2:3], 0, s[14:15]
	s_add_u32 s14, s38, 0x40080
	s_mov_b32 m0, s78
	s_addc_u32 s15, s39, 0
	global_load_lds_dwordx4 v[0:1], off
	s_add_i32 m0, s29, 0x1c000
	s_nop 0
	global_load_lds_dwordx4 v138, s[14:15]
	s_add_i32 m0, s29, 0x1e000
	s_cmpk_lt_u32 s10, 0x100
	global_load_lds_dwordx4 v142, s[14:15]
	v_lshrrev_b32_e32 v1, 1, v8
	v_and_b32_e32 v1, 24, v1
	v_and_b32_e32 v0, 15, v8
	v_lshlrev_b32_e32 v2, 1, v1
	v_lshl_or_b32 v170, s0, 6, v0
	v_lshl_or_b32 v0, v0, 6, v2
	v_lshlrev_b32_e32 v2, 2, v8
	v_and_b32_e32 v2, 32, v2
	v_bitop3_b32 v3, v0, s1, v2 bitop3:0xde
	v_bitop3_b32 v171, v0, s18, v2 bitop3:0xde
	v_lshlrev_b32_e32 v0, 14, v9
	v_and_b32_e32 v0, 0xffff8000, v0
	v_lshlrev_b32_e32 v144, 2, v1
	v_lshl_or_b32 v179, s16, 5, v1
	v_lshl_or_b32 v180, s16, 6, v1
	v_lshl_add_u32 v0, v10, 11, v0
	v_and_b32_e32 v1, 1, v9
	v_lshl_or_b32 v0, v1, 6, v0
	v_lshl_add_u64 v[146:147], s[52:53], 0, v[144:145]
	v_lshl_add_u64 v[148:149], s[50:51], 0, v[144:145]
	v_lshl_add_u32 v144, v11, 1, v0
	v_lshlrev_b32_e32 v0, 14, v12
	v_and_b32_e32 v0, 0xffff8000, v0
	v_lshl_add_u32 v0, v13, 11, v0
	v_and_b32_e32 v1, 1, v12
	s_mov_b64 s[0:1], 0x40080
	s_waitcnt vmcnt(6)
	v_lshl_or_b32 v0, v1, 6, v0
	v_lshl_add_u64 v[150:151], v[144:145], 0, s[0:1]
	v_lshl_add_u32 v144, v14, 1, v0
	s_cselect_b64 s[14:15], -1, 0
	v_or_b32_e32 v172, 16, v170
	v_or_b32_e32 v173, 32, v170
	v_or_b32_e32 v174, 48, v170
	v_add_u32_e32 v175, 0x80, v170
	v_add_u32_e32 v176, 0x90, v170
	v_add_u32_e32 v177, 0xa0, v170
	v_add_u32_e32 v178, 0xb0, v170
	s_ashr_i32 s79, s3, 31
	s_ashr_i32 s80, s2, 31
	v_lshl_add_u64 v[152:153], v[144:145], 0, s[0:1]
	v_mov_b64_e32 v[154:155], 0xb00
	v_mov_b64_e32 v[156:157], 0xaff
	s_movk_i32 s81, 0x161
	s_add_i32 s82, 0, 0x10000
	s_add_i32 s83, 0, 0x14000
	v_add_u32_e32 v181, 0, v3
	s_movk_i32 s84, 0x2c00
	v_mov_b32_e32 v182, 0x358637bd
	s_mov_b32 s16, 0x3e38aa3b
	s_mov_b32 s18, 0x3f317218
	s_mov_b32 s85, 0
	s_barrier
	s_branch .LBB0_159

.LBB0_162:
	v_add_u32_e32 v144, s82, v171
	ds_read_b128 v[132:135], v144
	ds_read_b128 v[158:161], v144 offset:1024
	ds_read_b128 v[162:165], v144 offset:2048
	ds_read_b128 v[166:169], v144 offset:3072
	v_add_u32_e32 v144, s83, v171
	ds_read_b128 v[184:187], v144
	ds_read_b128 v[188:191], v144 offset:1024
	ds_read_b128 v[192:195], v144 offset:2048
	ds_read_b128 v[196:199], v144 offset:3072
	s_add_u32 s10, s64, 0x100
	s_addc_u32 s95, s65, 0
	s_and_b64 s[64:65], exec, s[62:63]
	s_cselect_b32 s65, s23, s95
	s_cselect_b32 s64, s90, s10
	s_add_u32 s10, s94, 0x100
	s_addc_u32 s93, s93, 0
	s_and_b64 s[62:63], exec, s[62:63]
	s_cselect_b32 s63, s21, s93
	s_cselect_b32 s62, s91, s10
	v_lshl_add_u64 v[232:233], v[128:129], 0, s[56:57]
	s_add_i32 m0, s29, 0xc000
	ds_read_b128 v[200:203], v181
	ds_read_b128 v[204:207], v181 offset:1024
	ds_read_b128 v[208:211], v181 offset:2048
	ds_read_b128 v[212:215], v181 offset:3072
	ds_read_b128 v[216:219], v181 offset:4096
	ds_read_b128 v[220:223], v181 offset:5120
	ds_read_b128 v[224:227], v181 offset:6144
	ds_read_b128 v[228:231], v181 offset:7168
	global_load_lds_dwordx4 v[232:233], off
	v_lshl_add_u64 v[232:233], v[130:131], 0, s[56:57]
	s_add_i32 m0, s29, 0xe000
	s_nop 0
	global_load_lds_dwordx4 v[232:233], off
	s_waitcnt vmcnt(8)
	s_waitcnt lgkmcnt(0)
	s_barrier
	s_setprio 1
	s_waitcnt lgkmcnt(0)
	v_mfma_f32_16x16x32_bf16 v[124:127], v[132:135], v[200:203], v[124:127]
	v_mfma_f32_16x16x32_bf16 v[120:123], v[162:165], v[200:203], v[120:123]
	v_mfma_f32_16x16x32_bf16 v[108:111], v[132:135], v[208:211], v[108:111]
	v_mfma_f32_16x16x32_bf16 v[104:107], v[162:165], v[208:211], v[104:107]
	v_mfma_f32_16x16x32_bf16 v[92:95], v[132:135], v[216:219], v[92:95]
	v_mfma_f32_16x16x32_bf16 v[88:91], v[162:165], v[216:219], v[88:91]
	v_mfma_f32_16x16x32_bf16 v[76:79], v[132:135], v[224:227], v[76:79]
	v_mfma_f32_16x16x32_bf16 v[72:75], v[162:165], v[224:227], v[72:75]
	v_mfma_f32_16x16x32_bf16 v[124:127], v[158:161], v[204:207], v[124:127]
	v_mfma_f32_16x16x32_bf16 v[120:123], v[166:169], v[204:207], v[120:123]
	v_mfma_f32_16x16x32_bf16 v[108:111], v[158:161], v[212:215], v[108:111]
	v_mfma_f32_16x16x32_bf16 v[104:107], v[166:169], v[212:215], v[104:107]
	v_mfma_f32_16x16x32_bf16 v[92:95], v[158:161], v[220:223], v[92:95]
	v_mfma_f32_16x16x32_bf16 v[88:91], v[166:169], v[220:223], v[88:91]
	v_mfma_f32_16x16x32_bf16 v[76:79], v[158:161], v[228:231], v[76:79]
	v_mfma_f32_16x16x32_bf16 v[72:75], v[166:169], v[228:231], v[72:75]
	s_setprio 0
	s_setprio 1
	v_mfma_f32_16x16x32_bf16 v[116:119], v[184:187], v[200:203], v[116:119]
	v_mfma_f32_16x16x32_bf16 v[112:115], v[192:195], v[200:203], v[112:115]
	v_mfma_f32_16x16x32_bf16 v[100:103], v[184:187], v[208:211], v[100:103]
	v_mfma_f32_16x16x32_bf16 v[96:99], v[192:195], v[208:211], v[96:99]
	v_mfma_f32_16x16x32_bf16 v[84:87], v[184:187], v[216:219], v[84:87]
	v_mfma_f32_16x16x32_bf16 v[80:83], v[192:195], v[216:219], v[80:83]
	v_mfma_f32_16x16x32_bf16 v[68:71], v[184:187], v[224:227], v[68:71]
	v_mfma_f32_16x16x32_bf16 v[64:67], v[192:195], v[224:227], v[64:67]
	v_mfma_f32_16x16x32_bf16 v[116:119], v[188:191], v[204:207], v[116:119]
	v_mfma_f32_16x16x32_bf16 v[112:115], v[196:199], v[204:207], v[112:115]
	v_mfma_f32_16x16x32_bf16 v[100:103], v[188:191], v[212:215], v[100:103]
	v_mfma_f32_16x16x32_bf16 v[96:99], v[196:199], v[212:215], v[96:99]
	v_mfma_f32_16x16x32_bf16 v[84:87], v[188:191], v[220:223], v[84:87]
	v_mfma_f32_16x16x32_bf16 v[80:83], v[196:199], v[220:223], v[80:83]
	v_mfma_f32_16x16x32_bf16 v[68:71], v[188:191], v[228:231], v[68:71]
	v_mfma_f32_16x16x32_bf16 v[64:67], v[196:199], v[228:231], v[64:67]
	s_setprio 0
	s_barrier
	s_add_i32 s10, s82, s66
	s_mov_b32 m0, s10
	ds_read_b128 v[200:203], v181 offset:16384
	ds_read_b128 v[204:207], v181 offset:17408
	ds_read_b128 v[208:211], v181 offset:18432
	ds_read_b128 v[212:215], v181 offset:19456
	ds_read_b128 v[216:219], v181 offset:20480
	ds_read_b128 v[220:223], v181 offset:21504
	ds_read_b128 v[224:227], v181 offset:22528
	ds_read_b128 v[228:231], v181 offset:23552
	global_load_lds_dwordx4 v138, s[62:63]
	s_add_i32 m0, s10, 0x2000
	s_nop 0
	global_load_lds_dwordx4 v142, s[62:63]
	s_add_u32 s62, s62, 0x40000
	s_addc_u32 s63, s63, 0
	s_add_i32 s10, s83, s66
	s_mov_b32 m0, s10
	s_nop 0
	global_load_lds_dwordx4 v138, s[62:63]
	s_add_i32 m0, s10, 0x2000
	s_nop 0
	global_load_lds_dwordx4 v142, s[62:63]
	s_mov_b32 m0, s29
	s_nop 0
	global_load_lds_dwordx4 v136, s[64:65]
	s_mov_b32 m0, s31
	s_nop 0
	global_load_lds_dwordx4 v140, s[64:65]
	s_waitcnt vmcnt(8)
	s_waitcnt lgkmcnt(0)
	s_barrier
	s_setprio 1
	s_waitcnt lgkmcnt(0)
	v_mfma_f32_16x16x32_bf16 v[60:63], v[132:135], v[200:203], v[60:63]
	v_mfma_f32_16x16x32_bf16 v[56:59], v[162:165], v[200:203], v[56:59]
	v_mfma_f32_16x16x32_bf16 v[44:47], v[132:135], v[208:211], v[44:47]
	v_mfma_f32_16x16x32_bf16 v[40:43], v[162:165], v[208:211], v[40:43]
	v_mfma_f32_16x16x32_bf16 v[28:31], v[132:135], v[216:219], v[28:31]
	v_mfma_f32_16x16x32_bf16 v[24:27], v[162:165], v[216:219], v[24:27]
	v_mfma_f32_16x16x32_bf16 v[12:15], v[132:135], v[224:227], v[12:15]
	v_mfma_f32_16x16x32_bf16 v[8:11], v[162:165], v[224:227], v[8:11]
	v_mfma_f32_16x16x32_bf16 v[60:63], v[158:161], v[204:207], v[60:63]
	v_mfma_f32_16x16x32_bf16 v[56:59], v[166:169], v[204:207], v[56:59]
	v_mfma_f32_16x16x32_bf16 v[44:47], v[158:161], v[212:215], v[44:47]
	v_mfma_f32_16x16x32_bf16 v[40:43], v[166:169], v[212:215], v[40:43]
	v_mfma_f32_16x16x32_bf16 v[28:31], v[158:161], v[220:223], v[28:31]
	v_mfma_f32_16x16x32_bf16 v[24:27], v[166:169], v[220:223], v[24:27]
	v_mfma_f32_16x16x32_bf16 v[12:15], v[158:161], v[228:231], v[12:15]
	v_mfma_f32_16x16x32_bf16 v[8:11], v[166:169], v[228:231], v[8:11]
	s_setprio 0
	s_setprio 1
	v_mfma_f32_16x16x32_bf16 v[52:55], v[184:187], v[200:203], v[52:55]
	v_mfma_f32_16x16x32_bf16 v[48:51], v[192:195], v[200:203], v[48:51]
	v_mfma_f32_16x16x32_bf16 v[36:39], v[184:187], v[208:211], v[36:39]
	v_mfma_f32_16x16x32_bf16 v[32:35], v[192:195], v[208:211], v[32:35]
	v_mfma_f32_16x16x32_bf16 v[20:23], v[184:187], v[216:219], v[20:23]
	v_mfma_f32_16x16x32_bf16 v[16:19], v[192:195], v[216:219], v[16:19]
	v_mfma_f32_16x16x32_bf16 v[4:7], v[184:187], v[224:227], v[4:7]
	v_mfma_f32_16x16x32_bf16 v[0:3], v[192:195], v[224:227], v[0:3]
	v_mfma_f32_16x16x32_bf16 v[52:55], v[188:191], v[204:207], v[52:55]
	v_mfma_f32_16x16x32_bf16 v[48:51], v[196:199], v[204:207], v[48:51]
	v_mfma_f32_16x16x32_bf16 v[36:39], v[188:191], v[212:215], v[36:39]
	v_mfma_f32_16x16x32_bf16 v[32:35], v[196:199], v[212:215], v[32:35]
	v_mfma_f32_16x16x32_bf16 v[20:23], v[188:191], v[220:223], v[20:23]
	v_mfma_f32_16x16x32_bf16 v[16:19], v[196:199], v[220:223], v[16:19]
	v_mfma_f32_16x16x32_bf16 v[4:7], v[188:191], v[228:231], v[4:7]
	v_mfma_f32_16x16x32_bf16 v[0:3], v[196:199], v[228:231], v[0:3]
	s_setprio 0
	s_barrier
	s_add_i32 s10, 0, 0x18000
	v_add_u32_e32 v144, s10, v171
	s_add_i32 s93, 0, 0x1c000
	ds_read_b128 v[132:135], v144
	ds_read_b128 v[158:161], v144 offset:1024
	ds_read_b128 v[162:165], v144 offset:2048
	ds_read_b128 v[166:169], v144 offset:3072
	v_add_u32_e32 v144, s93, v171
	ds_read_b128 v[184:187], v144
	ds_read_b128 v[188:191], v144 offset:1024
	ds_read_b128 v[192:195], v144 offset:2048
	ds_read_b128 v[196:199], v144 offset:3072
	s_add_u32 s62, s64, 0x40000
	s_addc_u32 s63, s65, 0
	s_mov_b32 m0, s67
	ds_read_b128 v[200:203], v181 offset:32768
	ds_read_b128 v[204:207], v181 offset:33792
	ds_read_b128 v[208:211], v181 offset:34816
	ds_read_b128 v[212:215], v181 offset:35840
	ds_read_b128 v[216:219], v181 offset:36864
	ds_read_b128 v[220:223], v181 offset:37888
	ds_read_b128 v[224:227], v181 offset:38912
	ds_read_b128 v[228:231], v181 offset:39936
	global_load_lds_dwordx4 v136, s[62:63]
	s_mov_b32 m0, s68
	s_nop 0
	global_load_lds_dwordx4 v140, s[62:63]
	s_waitcnt vmcnt(8)
	s_waitcnt lgkmcnt(0)
	s_barrier
	s_setprio 1
	s_waitcnt lgkmcnt(0)
	v_mfma_f32_16x16x32_bf16 v[124:127], v[132:135], v[200:203], v[124:127]
	v_mfma_f32_16x16x32_bf16 v[120:123], v[162:165], v[200:203], v[120:123]
	v_mfma_f32_16x16x32_bf16 v[108:111], v[132:135], v[208:211], v[108:111]
	v_mfma_f32_16x16x32_bf16 v[104:107], v[162:165], v[208:211], v[104:107]
	v_mfma_f32_16x16x32_bf16 v[92:95], v[132:135], v[216:219], v[92:95]
	v_mfma_f32_16x16x32_bf16 v[88:91], v[162:165], v[216:219], v[88:91]
	v_mfma_f32_16x16x32_bf16 v[76:79], v[132:135], v[224:227], v[76:79]
	v_mfma_f32_16x16x32_bf16 v[72:75], v[162:165], v[224:227], v[72:75]
	v_mfma_f32_16x16x32_bf16 v[124:127], v[158:161], v[204:207], v[124:127]
	v_mfma_f32_16x16x32_bf16 v[120:123], v[166:169], v[204:207], v[120:123]
	v_mfma_f32_16x16x32_bf16 v[108:111], v[158:161], v[212:215], v[108:111]
	v_mfma_f32_16x16x32_bf16 v[104:107], v[166:169], v[212:215], v[104:107]
	v_mfma_f32_16x16x32_bf16 v[92:95], v[158:161], v[220:223], v[92:95]
	v_mfma_f32_16x16x32_bf16 v[88:91], v[166:169], v[220:223], v[88:91]
	v_mfma_f32_16x16x32_bf16 v[76:79], v[158:161], v[228:231], v[76:79]
	v_mfma_f32_16x16x32_bf16 v[72:75], v[166:169], v[228:231], v[72:75]
	s_setprio 0
	s_setprio 1
	v_mfma_f32_16x16x32_bf16 v[116:119], v[184:187], v[200:203], v[116:119]
	v_mfma_f32_16x16x32_bf16 v[112:115], v[192:195], v[200:203], v[112:115]
	v_mfma_f32_16x16x32_bf16 v[100:103], v[184:187], v[208:211], v[100:103]
	v_mfma_f32_16x16x32_bf16 v[96:99], v[192:195], v[208:211], v[96:99]
	v_mfma_f32_16x16x32_bf16 v[84:87], v[184:187], v[216:219], v[84:87]
	v_mfma_f32_16x16x32_bf16 v[80:83], v[192:195], v[216:219], v[80:83]
	v_mfma_f32_16x16x32_bf16 v[68:71], v[184:187], v[224:227], v[68:71]
	v_mfma_f32_16x16x32_bf16 v[64:67], v[192:195], v[224:227], v[64:67]
	v_mfma_f32_16x16x32_bf16 v[116:119], v[188:191], v[204:207], v[116:119]
	v_mfma_f32_16x16x32_bf16 v[112:115], v[196:199], v[204:207], v[112:115]
	v_mfma_f32_16x16x32_bf16 v[100:103], v[188:191], v[212:215], v[100:103]
	v_mfma_f32_16x16x32_bf16 v[96:99], v[196:199], v[212:215], v[96:99]
	v_mfma_f32_16x16x32_bf16 v[84:87], v[188:191], v[220:223], v[84:87]
	v_mfma_f32_16x16x32_bf16 v[80:83], v[196:199], v[220:223], v[80:83]
	v_mfma_f32_16x16x32_bf16 v[68:71], v[188:191], v[228:231], v[68:71]
	v_mfma_f32_16x16x32_bf16 v[64:67], v[196:199], v[228:231], v[64:67]
	s_setprio 0
	s_barrier
	s_add_i32 s10, s10, s66
	s_mov_b32 m0, s10
	ds_read_b128 v[200:203], v181 offset:49152
	ds_read_b128 v[204:207], v181 offset:50176
	ds_read_b128 v[208:211], v181 offset:51200
	ds_read_b128 v[212:215], v181 offset:52224
	ds_read_b128 v[216:219], v181 offset:53248
	ds_read_b128 v[220:223], v181 offset:54272
	ds_read_b128 v[224:227], v181 offset:55296
	ds_read_b128 v[228:231], v181 offset:56320
	global_load_lds_dwordx4 v138, s[60:61]
	s_add_i32 m0, s10, 0x2000
	s_nop 0
	global_load_lds_dwordx4 v142, s[60:61]
	s_add_u32 s60, s60, 0x40000
	s_addc_u32 s61, s61, 0
	s_add_i32 s10, s93, s66
	s_mov_b32 m0, s10
	s_nop 0
	global_load_lds_dwordx4 v138, s[60:61]
	s_add_i32 m0, s10, 0x2000
	s_nop 0
	global_load_lds_dwordx4 v142, s[60:61]
	s_mov_b32 m0, s73
	s_nop 0
	global_load_lds_dwordx4 v136, s[58:59]
	v_lshl_add_u64 v[232:233], s[58:59], 0, v[140:141]
	s_mov_b32 m0, s78
	s_nop 0
	global_load_lds_dwordx4 v[232:233], off
	s_waitcnt vmcnt(8)
	s_waitcnt lgkmcnt(0)
	s_barrier
	s_setprio 1
	s_waitcnt lgkmcnt(0)
	v_mfma_f32_16x16x32_bf16 v[60:63], v[132:135], v[200:203], v[60:63]
	v_mfma_f32_16x16x32_bf16 v[56:59], v[162:165], v[200:203], v[56:59]
	v_mfma_f32_16x16x32_bf16 v[44:47], v[132:135], v[208:211], v[44:47]
	v_mfma_f32_16x16x32_bf16 v[40:43], v[162:165], v[208:211], v[40:43]
	v_mfma_f32_16x16x32_bf16 v[28:31], v[132:135], v[216:219], v[28:31]
	v_mfma_f32_16x16x32_bf16 v[24:27], v[162:165], v[216:219], v[24:27]
	v_mfma_f32_16x16x32_bf16 v[12:15], v[132:135], v[224:227], v[12:15]
	v_mfma_f32_16x16x32_bf16 v[8:11], v[162:165], v[224:227], v[8:11]
	v_mfma_f32_16x16x32_bf16 v[60:63], v[158:161], v[204:207], v[60:63]
	v_mfma_f32_16x16x32_bf16 v[56:59], v[166:169], v[204:207], v[56:59]
	v_mfma_f32_16x16x32_bf16 v[44:47], v[158:161], v[212:215], v[44:47]
	v_mfma_f32_16x16x32_bf16 v[40:43], v[166:169], v[212:215], v[40:43]
	v_mfma_f32_16x16x32_bf16 v[28:31], v[158:161], v[220:223], v[28:31]
	v_mfma_f32_16x16x32_bf16 v[24:27], v[166:169], v[220:223], v[24:27]
	v_mfma_f32_16x16x32_bf16 v[12:15], v[158:161], v[228:231], v[12:15]
	v_mfma_f32_16x16x32_bf16 v[8:11], v[166:169], v[228:231], v[8:11]
	s_setprio 0
	s_setprio 1
	v_mfma_f32_16x16x32_bf16 v[52:55], v[184:187], v[200:203], v[52:55]
	v_mfma_f32_16x16x32_bf16 v[48:51], v[192:195], v[200:203], v[48:51]
	v_mfma_f32_16x16x32_bf16 v[36:39], v[184:187], v[208:211], v[36:39]
	v_mfma_f32_16x16x32_bf16 v[32:35], v[192:195], v[208:211], v[32:35]
	v_mfma_f32_16x16x32_bf16 v[20:23], v[184:187], v[216:219], v[20:23]
	v_mfma_f32_16x16x32_bf16 v[16:19], v[192:195], v[216:219], v[16:19]
	v_mfma_f32_16x16x32_bf16 v[4:7], v[184:187], v[224:227], v[4:7]
	v_mfma_f32_16x16x32_bf16 v[0:3], v[192:195], v[224:227], v[0:3]
	v_mfma_f32_16x16x32_bf16 v[52:55], v[188:191], v[204:207], v[52:55]
	v_mfma_f32_16x16x32_bf16 v[48:51], v[196:199], v[204:207], v[48:51]
	v_mfma_f32_16x16x32_bf16 v[36:39], v[188:191], v[212:215], v[36:39]
	v_mfma_f32_16x16x32_bf16 v[32:35], v[196:199], v[212:215], v[32:35]
	v_mfma_f32_16x16x32_bf16 v[20:23], v[188:191], v[220:223], v[20:23]
	v_mfma_f32_16x16x32_bf16 v[16:19], v[196:199], v[220:223], v[16:19]
	v_mfma_f32_16x16x32_bf16 v[4:7], v[188:191], v[228:231], v[4:7]
	v_mfma_f32_16x16x32_bf16 v[0:3], v[196:199], v[228:231], v[0:3]
	s_setprio 0
	s_barrier
	s_add_i32 s10, s92, 2
	s_add_u32 s56, s56, 0x100
	s_addc_u32 s57, s57, 0
	s_cmp_gt_u32 s92, 13
	s_mov_b32 s92, s10
	s_cbranch_scc1 .LBB0_169

.LBB0_600:
	s_add_u32 s66, s76, 0x7c00800
	s_addc_u32 s67, s77, 0
	s_add_u32 s68, s76, 0xc00000
	s_addc_u32 s69, s77, 0
	s_add_u32 s12, s76, 0x7c01c00
	s_addc_u32 s13, s77, 0
	s_add_u32 s14, s76, 0x7c02400
	s_addc_u32 s15, s77, 0
	s_lshl_b32 s0, s0, 5
	s_lshl_b32 s70, s1, 6
	s_lshl_b32 s4, s1, 13
	s_and_b32 s5, s0, 0x60
	s_mov_b64 s[0:1], 0x80
	s_add_i32 m0, s62, 0x18000
	v_lshl_add_u64 v[6:7], v[6:7], 0, s[0:1]
	s_waitcnt vmcnt(2)
	s_barrier
	global_load_lds_dwordx4 v[6:7], off
	v_lshl_add_u64 v[4:5], v[4:5], 0, s[0:1]
	s_add_i32 m0, s62, 0x1a000
	s_add_i32 s71, s62, 0x8000
	s_lshl_b32 s17, s5, 7
	global_load_lds_dwordx4 v[4:5], off
	v_lshl_add_u64 v[0:1], v[0:1], 0, s[0:1]
	s_mov_b32 m0, s71
	s_add_i32 s72, s62, 0xa000
	global_load_lds_dwordx4 v[0:1], off
	v_lshl_add_u64 v[0:1], v[2:3], 0, s[0:1]
	s_add_u32 s0, s26, 0x20080
	s_mov_b32 m0, s72
	s_addc_u32 s1, s27, 0
	global_load_lds_dwordx4 v[0:1], off
	s_add_i32 m0, s62, 0x1c000
	s_nop 0
	global_load_lds_dwordx4 v138, s[0:1]
	s_add_i32 m0, s62, 0x1e000
	v_and_b32_e32 v145, 15, v8
	global_load_lds_dwordx4 v142, s[0:1]
	v_lshrrev_b32_e32 v0, 1, v8
	v_and_b32_e32 v1, 24, v0
	v_lshlrev_b32_e32 v0, 1, v1
	v_lshlrev_b32_e32 v3, 2, v8
	v_lshl_or_b32 v2, v145, 6, v0
	v_and_b32_e32 v3, 32, v3
	s_cmpk_lt_u32 s16, 0x100
	v_bitop3_b32 v155, v2, s17, v3 bitop3:0xde
	s_cselect_b64 s[16:17], -1, 0
	s_ashr_i32 s73, s3, 31
	s_ashr_i32 s78, s2, 31
	s_lshl_b32 s0, s5, 1
	s_waitcnt vmcnt(6)
	s_add_u32 s0, s12, s0
	v_bitop3_b32 v4, v2, s4, v3 bitop3:0xde
	v_or_b32_e32 v144, s5, v1
	s_addc_u32 s1, s13, 0
	v_mov_b32_e32 v1, v139
	v_or_b32_e32 v154, s70, v145
	v_lshl_add_u64 v[146:147], s[0:1], 0, v[0:1]
	v_mov_b64_e32 v[148:149], 0x200
	v_mov_b64_e32 v[150:151], 0x1ff
	s_add_i32 s79, 0, 0x10000
	s_add_i32 s80, 0, 0x14000
	v_add_u32_e32 v156, 0, v4
	s_movk_i32 s81, 0x2c00
	s_mov_b32 s82, 0
	s_barrier
	s_branch .LBB0_603

.LBB0_612:
	s_cmp_lt_u32 s95, 8
	v_add_u32_e32 v157, s79, v155
	s_cselect_b64 s[56:57], -1, 0
	ds_read_b128 v[128:131], v157
	ds_read_b128 v[132:135], v157 offset:1024
	ds_read_b128 v[158:161], v157 offset:2048
	ds_read_b128 v[162:165], v157 offset:3072
	v_add_u32_e32 v157, s80, v155
	s_and_b64 s[96:97], s[56:57], exec
	ds_read_b128 v[166:169], v157
	ds_read_b128 v[170:173], v157 offset:1024
	ds_read_b128 v[174:177], v157 offset:2048
	ds_read_b128 v[178:181], v157 offset:3072
	s_cselect_b32 s8, 0, -8
	s_add_i32 s8, s8, s95
	s_add_i32 s8, s8, 1
	s_and_b64 s[56:57], s[56:57], exec
	s_cselect_b32 s96, s29, s85
	s_cselect_b32 s97, s28, s84
	s_lshl_b64 s[56:57], s[8:9], 7
	s_add_u32 s8, s97, s56
	s_addc_u32 s57, s96, s57
	s_add_u32 s56, s8, 0x160000
	s_addc_u32 s57, s57, 0
	s_add_i32 m0, s62, 0xc000
	ds_read_b128 v[182:185], v156
	ds_read_b128 v[186:189], v156 offset:1024
	ds_read_b128 v[190:193], v156 offset:2048
	ds_read_b128 v[194:197], v156 offset:3072
	ds_read_b128 v[198:201], v156 offset:4096
	ds_read_b128 v[202:205], v156 offset:5120
	ds_read_b128 v[206:209], v156 offset:6144
	ds_read_b128 v[210:213], v156 offset:7168
	global_load_lds_dwordx4 v136, s[56:57]
	s_add_i32 m0, s62, 0xe000
	s_nop 0
	global_load_lds_dwordx4 v140, s[56:57]
	s_waitcnt vmcnt(8)
	s_waitcnt lgkmcnt(0)
	s_barrier
	s_setprio 1
	s_waitcnt lgkmcnt(0)
	v_mfma_f32_16x16x32_bf16 v[124:127], v[128:131], v[182:185], v[124:127]
	v_mfma_f32_16x16x32_bf16 v[120:123], v[158:161], v[182:185], v[120:123]
	v_mfma_f32_16x16x32_bf16 v[112:115], v[128:131], v[190:193], v[112:115]
	v_mfma_f32_16x16x32_bf16 v[104:107], v[158:161], v[190:193], v[104:107]
	v_mfma_f32_16x16x32_bf16 v[96:99], v[128:131], v[198:201], v[96:99]
	v_mfma_f32_16x16x32_bf16 v[88:91], v[158:161], v[198:201], v[88:91]
	v_mfma_f32_16x16x32_bf16 v[80:83], v[128:131], v[206:209], v[80:83]
	v_mfma_f32_16x16x32_bf16 v[72:75], v[158:161], v[206:209], v[72:75]
	v_mfma_f32_16x16x32_bf16 v[124:127], v[132:135], v[186:189], v[124:127]
	v_mfma_f32_16x16x32_bf16 v[120:123], v[162:165], v[186:189], v[120:123]
	v_mfma_f32_16x16x32_bf16 v[112:115], v[132:135], v[194:197], v[112:115]
	v_mfma_f32_16x16x32_bf16 v[104:107], v[162:165], v[194:197], v[104:107]
	v_mfma_f32_16x16x32_bf16 v[96:99], v[132:135], v[202:205], v[96:99]
	v_mfma_f32_16x16x32_bf16 v[88:91], v[162:165], v[202:205], v[88:91]
	v_mfma_f32_16x16x32_bf16 v[80:83], v[132:135], v[210:213], v[80:83]
	v_mfma_f32_16x16x32_bf16 v[72:75], v[162:165], v[210:213], v[72:75]
	s_setprio 0
	s_setprio 1
	v_mfma_f32_16x16x32_bf16 v[116:119], v[166:169], v[182:185], v[116:119]
	v_mfma_f32_16x16x32_bf16 v[108:111], v[174:177], v[182:185], v[108:111]
	v_mfma_f32_16x16x32_bf16 v[100:103], v[166:169], v[190:193], v[100:103]
	v_mfma_f32_16x16x32_bf16 v[92:95], v[174:177], v[190:193], v[92:95]
	v_mfma_f32_16x16x32_bf16 v[84:87], v[166:169], v[198:201], v[84:87]
	v_mfma_f32_16x16x32_bf16 v[76:79], v[174:177], v[198:201], v[76:79]
	v_mfma_f32_16x16x32_bf16 v[68:71], v[166:169], v[206:209], v[68:71]
	v_mfma_f32_16x16x32_bf16 v[64:67], v[174:177], v[206:209], v[64:67]
	v_mfma_f32_16x16x32_bf16 v[116:119], v[170:173], v[186:189], v[116:119]
	v_mfma_f32_16x16x32_bf16 v[108:111], v[178:181], v[186:189], v[108:111]
	v_mfma_f32_16x16x32_bf16 v[100:103], v[170:173], v[194:197], v[100:103]
	v_mfma_f32_16x16x32_bf16 v[92:95], v[178:181], v[194:197], v[92:95]
	v_mfma_f32_16x16x32_bf16 v[84:87], v[170:173], v[202:205], v[84:87]
	v_mfma_f32_16x16x32_bf16 v[76:79], v[178:181], v[202:205], v[76:79]
	v_mfma_f32_16x16x32_bf16 v[68:71], v[170:173], v[210:213], v[68:71]
	v_mfma_f32_16x16x32_bf16 v[64:67], v[178:181], v[210:213], v[64:67]
	s_setprio 0
	s_barrier
	s_add_i32 s8, s79, s61
	s_mov_b32 m0, s8
	ds_read_b128 v[182:185], v156 offset:16384
	ds_read_b128 v[186:189], v156 offset:17408
	ds_read_b128 v[190:193], v156 offset:18432
	ds_read_b128 v[194:197], v156 offset:19456
	ds_read_b128 v[198:201], v156 offset:20480
	ds_read_b128 v[202:205], v156 offset:21504
	ds_read_b128 v[206:209], v156 offset:22528
	ds_read_b128 v[210:213], v156 offset:23552
	global_load_lds_dwordx4 v138, s[54:55]
	s_add_i32 m0, s8, 0x2000
	s_nop 0
	global_load_lds_dwordx4 v142, s[54:55]
	s_add_u32 s54, s54, 0x20000
	s_addc_u32 s55, s55, 0
	s_add_i32 s8, s80, s61
	s_mov_b32 m0, s8
	s_nop 0
	global_load_lds_dwordx4 v138, s[54:55]
	s_add_i32 m0, s8, 0x2000
	s_nop 0
	global_load_lds_dwordx4 v142, s[54:55]
	s_mov_b32 m0, s62
	s_nop 0
	global_load_lds_dwordx4 v136, s[50:51]
	s_mov_b32 m0, s63
	s_nop 0
	global_load_lds_dwordx4 v140, s[50:51]
	s_waitcnt vmcnt(8)
	s_waitcnt lgkmcnt(0)
	s_barrier
	s_setprio 1
	s_waitcnt lgkmcnt(0)
	v_mfma_f32_16x16x32_bf16 v[60:63], v[128:131], v[182:185], v[60:63]
	v_mfma_f32_16x16x32_bf16 v[56:59], v[158:161], v[182:185], v[56:59]
	v_mfma_f32_16x16x32_bf16 v[48:51], v[128:131], v[190:193], v[48:51]
	v_mfma_f32_16x16x32_bf16 v[40:43], v[158:161], v[190:193], v[40:43]
	v_mfma_f32_16x16x32_bf16 v[32:35], v[128:131], v[198:201], v[32:35]
	v_mfma_f32_16x16x32_bf16 v[24:27], v[158:161], v[198:201], v[24:27]
	v_mfma_f32_16x16x32_bf16 v[16:19], v[128:131], v[206:209], v[16:19]
	v_mfma_f32_16x16x32_bf16 v[8:11], v[158:161], v[206:209], v[8:11]
	v_mfma_f32_16x16x32_bf16 v[60:63], v[132:135], v[186:189], v[60:63]
	v_mfma_f32_16x16x32_bf16 v[56:59], v[162:165], v[186:189], v[56:59]
	v_mfma_f32_16x16x32_bf16 v[48:51], v[132:135], v[194:197], v[48:51]
	v_mfma_f32_16x16x32_bf16 v[40:43], v[162:165], v[194:197], v[40:43]
	v_mfma_f32_16x16x32_bf16 v[32:35], v[132:135], v[202:205], v[32:35]
	v_mfma_f32_16x16x32_bf16 v[24:27], v[162:165], v[202:205], v[24:27]
	v_mfma_f32_16x16x32_bf16 v[16:19], v[132:135], v[210:213], v[16:19]
	v_mfma_f32_16x16x32_bf16 v[8:11], v[162:165], v[210:213], v[8:11]
	s_setprio 0
	s_setprio 1
	v_mfma_f32_16x16x32_bf16 v[52:55], v[166:169], v[182:185], v[52:55]
	v_mfma_f32_16x16x32_bf16 v[44:47], v[174:177], v[182:185], v[44:47]
	v_mfma_f32_16x16x32_bf16 v[36:39], v[166:169], v[190:193], v[36:39]
	v_mfma_f32_16x16x32_bf16 v[28:31], v[174:177], v[190:193], v[28:31]
	v_mfma_f32_16x16x32_bf16 v[20:23], v[166:169], v[198:201], v[20:23]
	v_mfma_f32_16x16x32_bf16 v[12:15], v[174:177], v[198:201], v[12:15]
	v_mfma_f32_16x16x32_bf16 v[4:7], v[166:169], v[206:209], v[4:7]
	v_mfma_f32_16x16x32_bf16 v[0:3], v[174:177], v[206:209], v[0:3]
	v_mfma_f32_16x16x32_bf16 v[52:55], v[170:173], v[186:189], v[52:55]
	v_mfma_f32_16x16x32_bf16 v[44:47], v[178:181], v[186:189], v[44:47]
	v_mfma_f32_16x16x32_bf16 v[36:39], v[170:173], v[194:197], v[36:39]
	v_mfma_f32_16x16x32_bf16 v[28:31], v[178:181], v[194:197], v[28:31]
	v_mfma_f32_16x16x32_bf16 v[20:23], v[170:173], v[202:205], v[20:23]
	v_mfma_f32_16x16x32_bf16 v[12:15], v[178:181], v[202:205], v[12:15]
	v_mfma_f32_16x16x32_bf16 v[4:7], v[170:173], v[210:213], v[4:7]
	v_mfma_f32_16x16x32_bf16 v[0:3], v[178:181], v[210:213], v[0:3]
	s_setprio 0
	s_barrier
	s_add_i32 s8, 0, 0x18000
	v_add_u32_e32 v157, s8, v155
	s_add_i32 s54, 0, 0x1c000
	ds_read_b128 v[128:131], v157
	ds_read_b128 v[132:135], v157 offset:1024
	ds_read_b128 v[158:161], v157 offset:2048
	ds_read_b128 v[162:165], v157 offset:3072
	v_add_u32_e32 v157, s54, v155
	ds_read_b128 v[166:169], v157
	ds_read_b128 v[170:173], v157 offset:1024
	ds_read_b128 v[174:177], v157 offset:2048
	ds_read_b128 v[178:181], v157 offset:3072
	s_add_u32 s50, s50, 0x160000
	s_addc_u32 s51, s51, 0
	s_mov_b32 m0, s64
	ds_read_b128 v[182:185], v156 offset:32768
	ds_read_b128 v[186:189], v156 offset:33792
	ds_read_b128 v[190:193], v156 offset:34816
	ds_read_b128 v[194:197], v156 offset:35840
	ds_read_b128 v[198:201], v156 offset:36864
	ds_read_b128 v[202:205], v156 offset:37888
	ds_read_b128 v[206:209], v156 offset:38912
	ds_read_b128 v[210:213], v156 offset:39936
	global_load_lds_dwordx4 v136, s[50:51]
	s_mov_b32 m0, s65
	s_nop 0
	global_load_lds_dwordx4 v140, s[50:51]
	s_waitcnt vmcnt(8)
	s_waitcnt lgkmcnt(0)
	s_barrier
	s_setprio 1
	s_waitcnt lgkmcnt(0)
	v_mfma_f32_16x16x32_bf16 v[124:127], v[128:131], v[182:185], v[124:127]
	v_mfma_f32_16x16x32_bf16 v[120:123], v[158:161], v[182:185], v[120:123]
	v_mfma_f32_16x16x32_bf16 v[112:115], v[128:131], v[190:193], v[112:115]
	v_mfma_f32_16x16x32_bf16 v[104:107], v[158:161], v[190:193], v[104:107]
	v_mfma_f32_16x16x32_bf16 v[96:99], v[128:131], v[198:201], v[96:99]
	v_mfma_f32_16x16x32_bf16 v[88:91], v[158:161], v[198:201], v[88:91]
	v_mfma_f32_16x16x32_bf16 v[80:83], v[128:131], v[206:209], v[80:83]
	v_mfma_f32_16x16x32_bf16 v[72:75], v[158:161], v[206:209], v[72:75]
	v_mfma_f32_16x16x32_bf16 v[124:127], v[132:135], v[186:189], v[124:127]
	v_mfma_f32_16x16x32_bf16 v[120:123], v[162:165], v[186:189], v[120:123]
	v_mfma_f32_16x16x32_bf16 v[112:115], v[132:135], v[194:197], v[112:115]
	v_mfma_f32_16x16x32_bf16 v[104:107], v[162:165], v[194:197], v[104:107]
	v_mfma_f32_16x16x32_bf16 v[96:99], v[132:135], v[202:205], v[96:99]
	v_mfma_f32_16x16x32_bf16 v[88:91], v[162:165], v[202:205], v[88:91]
	v_mfma_f32_16x16x32_bf16 v[80:83], v[132:135], v[210:213], v[80:83]
	v_mfma_f32_16x16x32_bf16 v[72:75], v[162:165], v[210:213], v[72:75]
	s_setprio 0
	s_setprio 1
	v_mfma_f32_16x16x32_bf16 v[116:119], v[166:169], v[182:185], v[116:119]
	v_mfma_f32_16x16x32_bf16 v[108:111], v[174:177], v[182:185], v[108:111]
	v_mfma_f32_16x16x32_bf16 v[100:103], v[166:169], v[190:193], v[100:103]
	v_mfma_f32_16x16x32_bf16 v[92:95], v[174:177], v[190:193], v[92:95]
	v_mfma_f32_16x16x32_bf16 v[84:87], v[166:169], v[198:201], v[84:87]
	v_mfma_f32_16x16x32_bf16 v[76:79], v[174:177], v[198:201], v[76:79]
	v_mfma_f32_16x16x32_bf16 v[68:71], v[166:169], v[206:209], v[68:71]
	v_mfma_f32_16x16x32_bf16 v[64:67], v[174:177], v[206:209], v[64:67]
	v_mfma_f32_16x16x32_bf16 v[116:119], v[170:173], v[186:189], v[116:119]
	v_mfma_f32_16x16x32_bf16 v[108:111], v[178:181], v[186:189], v[108:111]
	v_mfma_f32_16x16x32_bf16 v[100:103], v[170:173], v[194:197], v[100:103]
	v_mfma_f32_16x16x32_bf16 v[92:95], v[178:181], v[194:197], v[92:95]
	v_mfma_f32_16x16x32_bf16 v[84:87], v[170:173], v[202:205], v[84:87]
	v_mfma_f32_16x16x32_bf16 v[76:79], v[178:181], v[202:205], v[76:79]
	v_mfma_f32_16x16x32_bf16 v[68:71], v[170:173], v[210:213], v[68:71]
	v_mfma_f32_16x16x32_bf16 v[64:67], v[178:181], v[210:213], v[64:67]
	s_setprio 0
	s_barrier
	s_add_i32 s8, s8, s61
	s_mov_b32 m0, s8
	ds_read_b128 v[182:185], v156 offset:49152
	ds_read_b128 v[186:189], v156 offset:50176
	ds_read_b128 v[190:193], v156 offset:51200
	ds_read_b128 v[194:197], v156 offset:52224
	ds_read_b128 v[198:201], v156 offset:53248
	ds_read_b128 v[202:205], v156 offset:54272
	ds_read_b128 v[206:209], v156 offset:55296
	ds_read_b128 v[210:213], v156 offset:56320
	global_load_lds_dwordx4 v138, s[4:5]
	s_add_i32 m0, s8, 0x2000
	s_nop 0
	global_load_lds_dwordx4 v142, s[4:5]
	s_add_u32 s4, s4, 0x20000
	s_addc_u32 s5, s5, 0
	s_add_i32 s8, s54, s61
	s_mov_b32 m0, s8
	s_nop 0
	global_load_lds_dwordx4 v138, s[4:5]
	s_add_i32 m0, s8, 0x2000
	s_nop 0
	global_load_lds_dwordx4 v142, s[4:5]
	s_mov_b32 m0, s71
	s_nop 0
	global_load_lds_dwordx4 v136, s[52:53]
	s_mov_b32 m0, s72
	s_nop 0
	global_load_lds_dwordx4 v140, s[52:53]
	s_waitcnt vmcnt(8)
	s_waitcnt lgkmcnt(0)
	s_barrier
	s_setprio 1
	s_waitcnt lgkmcnt(0)
	v_mfma_f32_16x16x32_bf16 v[60:63], v[128:131], v[182:185], v[60:63]
	v_mfma_f32_16x16x32_bf16 v[56:59], v[158:161], v[182:185], v[56:59]
	v_mfma_f32_16x16x32_bf16 v[48:51], v[128:131], v[190:193], v[48:51]
	v_mfma_f32_16x16x32_bf16 v[40:43], v[158:161], v[190:193], v[40:43]
	v_mfma_f32_16x16x32_bf16 v[32:35], v[128:131], v[198:201], v[32:35]
	v_mfma_f32_16x16x32_bf16 v[24:27], v[158:161], v[198:201], v[24:27]
	v_mfma_f32_16x16x32_bf16 v[16:19], v[128:131], v[206:209], v[16:19]
	v_mfma_f32_16x16x32_bf16 v[8:11], v[158:161], v[206:209], v[8:11]
	v_mfma_f32_16x16x32_bf16 v[60:63], v[132:135], v[186:189], v[60:63]
	v_mfma_f32_16x16x32_bf16 v[56:59], v[162:165], v[186:189], v[56:59]
	v_mfma_f32_16x16x32_bf16 v[48:51], v[132:135], v[194:197], v[48:51]
	v_mfma_f32_16x16x32_bf16 v[40:43], v[162:165], v[194:197], v[40:43]
	v_mfma_f32_16x16x32_bf16 v[32:35], v[132:135], v[202:205], v[32:35]
	v_mfma_f32_16x16x32_bf16 v[24:27], v[162:165], v[202:205], v[24:27]
	v_mfma_f32_16x16x32_bf16 v[16:19], v[132:135], v[210:213], v[16:19]
	v_mfma_f32_16x16x32_bf16 v[8:11], v[162:165], v[210:213], v[8:11]
	s_setprio 0
	s_setprio 1
	v_mfma_f32_16x16x32_bf16 v[52:55], v[166:169], v[182:185], v[52:55]
	v_mfma_f32_16x16x32_bf16 v[44:47], v[174:177], v[182:185], v[44:47]
	v_mfma_f32_16x16x32_bf16 v[36:39], v[166:169], v[190:193], v[36:39]
	v_mfma_f32_16x16x32_bf16 v[28:31], v[174:177], v[190:193], v[28:31]
	v_mfma_f32_16x16x32_bf16 v[20:23], v[166:169], v[198:201], v[20:23]
	v_mfma_f32_16x16x32_bf16 v[12:15], v[174:177], v[198:201], v[12:15]
	v_mfma_f32_16x16x32_bf16 v[4:7], v[166:169], v[206:209], v[4:7]
	v_mfma_f32_16x16x32_bf16 v[0:3], v[174:177], v[206:209], v[0:3]
	v_mfma_f32_16x16x32_bf16 v[52:55], v[170:173], v[186:189], v[52:55]
	v_mfma_f32_16x16x32_bf16 v[44:47], v[178:181], v[186:189], v[44:47]
	v_mfma_f32_16x16x32_bf16 v[36:39], v[170:173], v[194:197], v[36:39]
	v_mfma_f32_16x16x32_bf16 v[28:31], v[178:181], v[194:197], v[28:31]
	v_mfma_f32_16x16x32_bf16 v[20:23], v[170:173], v[202:205], v[20:23]
	v_mfma_f32_16x16x32_bf16 v[12:15], v[178:181], v[202:205], v[12:15]
	v_mfma_f32_16x16x32_bf16 v[4:7], v[170:173], v[210:213], v[4:7]
	v_mfma_f32_16x16x32_bf16 v[0:3], v[178:181], v[210:213], v[0:3]
	s_setprio 0
	s_barrier
	s_add_i32 s4, s95, 2
	s_add_u32 s48, s48, 0x100
	s_addc_u32 s49, s49, 0
	s_cmp_gt_u32 s95, 13
	s_mov_b32 s95, s4
	s_cbranch_scc1 .LBB0_635

.LBB0_704:
	s_add_u32 s63, s76, 0x2c00800
	s_addc_u32 s64, s77, 0
	s_add_u32 s65, s76, 0xe00800
	s_addc_u32 s66, s77, 0
	s_add_u32 s14, s76, 0x2800000
	s_mov_b64 s[4:5], 0x80
	s_addc_u32 s15, s77, 0
	s_add_i32 m0, s59, 0x18000
	v_lshl_add_u64 v[6:7], v[6:7], 0, s[4:5]
	s_and_b32 s67, s0, 3
	s_waitcnt vmcnt(2)
	s_barrier
	global_load_lds_dwordx4 v[6:7], off
	v_lshl_add_u64 v[4:5], v[4:5], 0, s[4:5]
	s_add_i32 m0, s59, 0x1a000
	s_add_i32 s68, s59, 0x8000
	s_lshl_b32 s0, s1, 13
	s_lshl_b32 s20, s67, 5
	s_lshl_b32 s16, s67, 12
	global_load_lds_dwordx4 v[4:5], off
	v_lshl_add_u64 v[0:1], v[0:1], 0, s[4:5]
	s_mov_b32 m0, s68
	s_add_i32 s69, s59, 0xa000
	global_load_lds_dwordx4 v[0:1], off
	v_lshl_add_u64 v[0:1], v[2:3], 0, s[4:5]
	s_add_u32 s4, s38, 0x40080
	s_mov_b32 m0, s69
	s_addc_u32 s5, s39, 0
	global_load_lds_dwordx4 v[0:1], off
	s_add_i32 m0, s59, 0x1c000
	s_nop 0
	global_load_lds_dwordx4 v146, s[4:5]
	s_add_i32 m0, s59, 0x1e000
	v_and_b32_e32 v2, 15, v8
	global_load_lds_dwordx4 v150, s[4:5]
	v_bfe_u32 v1, v8, 4, 2
	v_lshlrev_b32_e32 v3, 4, v1
	v_lshl_or_b32 v170, s1, 6, v2
	v_lshl_or_b32 v2, v2, 6, v3
	v_lshlrev_b32_e32 v3, 2, v8
	v_and_b32_e32 v3, 32, v3
	v_lshlrev_b32_e32 v0, 3, v1
	v_bitop3_b32 v4, v2, s0, v3 bitop3:0xde
	s_cmpk_lt_u32 s10, 0x100
	v_cmp_eq_u32_e64 s[0:1], 0, v1
	v_lshlrev_b32_e32 v152, 5, v1
	v_lshlrev_b32_e32 v1, 14, v9
	v_bitop3_b32 v171, v2, s16, v3 bitop3:0xde
	s_cselect_b64 s[16:17], -1, 0
	s_ashr_i32 s70, s3, 31
	s_ashr_i32 s71, s2, 31
	s_lshl_b32 s10, s67, 7
	v_and_b32_e32 v1, 0xffff8000, v1
	s_add_u32 s18, s36, s10
	v_lshl_add_u32 v1, v10, 11, v1
	v_and_b32_e32 v2, 1, v9
	s_addc_u32 s19, s37, 0
	v_lshl_or_b32 v1, v2, 6, v1
	v_lshl_add_u64 v[154:155], s[18:19], 0, v[152:153]
	v_lshl_add_u32 v152, v11, 1, v1
	v_lshlrev_b32_e32 v1, 14, v12
	v_and_b32_e32 v1, 0xffff8000, v1
	v_lshl_add_u32 v1, v13, 11, v1
	v_and_b32_e32 v2, 1, v12
	s_mov_b64 s[4:5], 0x40080
	s_waitcnt vmcnt(6)
	v_lshl_or_b32 v1, v2, 6, v1
	v_lshl_add_u64 v[156:157], v[152:153], 0, s[4:5]
	v_lshl_add_u32 v152, v14, 1, v1
	v_lshl_add_u64 v[158:159], v[152:153], 0, s[4:5]
	v_mov_b64_e32 v[160:161], 0x200
	v_mov_b64_e32 v[162:163], 0x1ff
	s_add_i32 s72, 0, 0x10000
	s_add_i32 s73, 0, 0x14000
	v_add_u32_e32 v172, 0, v4
	s_lshl_b32 s18, s20, 1
	v_lshlrev_b32_e32 v152, 1, v0
	s_mov_b32 s78, 0
	s_barrier
	s_branch .LBB0_707

.LBB0_714:
	v_add_u32_e32 v164, s72, v171
	v_add_u32_e32 v168, s73, v171
	ds_read_b128 v[132:135], v164
	ds_read_b128 v[136:139], v164 offset:1024
	ds_read_b128 v[140:143], v164 offset:2048
	ds_read_b128 v[164:167], v164 offset:3072
	ds_read_b128 v[174:177], v168
	ds_read_b128 v[178:181], v168 offset:1024
	ds_read_b128 v[182:185], v168 offset:2048
	ds_read_b128 v[186:189], v168 offset:3072
	s_add_u32 s10, s56, 0x100
	s_addc_u32 s85, s57, 0
	s_and_b64 s[56:57], exec, s[54:55]
	s_cselect_b32 s57, s23, s85
	s_cselect_b32 s56, s80, s10
	s_add_u32 s10, s84, 0x100
	s_addc_u32 s83, s83, 0
	s_and_b64 s[54:55], exec, s[54:55]
	s_cselect_b32 s55, s21, s83
	s_cselect_b32 s54, s81, s10
	v_lshl_add_u64 v[168:169], v[128:129], 0, s[48:49]
	s_add_i32 m0, s59, 0xc000
	ds_read_b128 v[190:193], v172
	ds_read_b128 v[194:197], v172 offset:1024
	ds_read_b128 v[198:201], v172 offset:2048
	ds_read_b128 v[202:205], v172 offset:3072
	ds_read_b128 v[206:209], v172 offset:4096
	ds_read_b128 v[210:213], v172 offset:5120
	ds_read_b128 v[214:217], v172 offset:6144
	ds_read_b128 v[218:221], v172 offset:7168
	global_load_lds_dwordx4 v[168:169], off
	v_lshl_add_u64 v[168:169], v[130:131], 0, s[48:49]
	s_add_i32 m0, s59, 0xe000
	s_nop 0
	global_load_lds_dwordx4 v[168:169], off
	s_waitcnt vmcnt(8)
	s_waitcnt lgkmcnt(0)
	s_barrier
	s_setprio 1
	s_waitcnt lgkmcnt(0)
	v_mfma_f32_16x16x32_bf16 v[124:127], v[132:135], v[190:193], v[124:127]
	v_mfma_f32_16x16x32_bf16 v[120:123], v[140:143], v[190:193], v[120:123]
	v_mfma_f32_16x16x32_bf16 v[108:111], v[132:135], v[198:201], v[108:111]
	v_mfma_f32_16x16x32_bf16 v[104:107], v[140:143], v[198:201], v[104:107]
	v_mfma_f32_16x16x32_bf16 v[92:95], v[132:135], v[206:209], v[92:95]
	v_mfma_f32_16x16x32_bf16 v[88:91], v[140:143], v[206:209], v[88:91]
	v_mfma_f32_16x16x32_bf16 v[76:79], v[132:135], v[214:217], v[76:79]
	v_mfma_f32_16x16x32_bf16 v[72:75], v[140:143], v[214:217], v[72:75]
	v_mfma_f32_16x16x32_bf16 v[124:127], v[136:139], v[194:197], v[124:127]
	v_mfma_f32_16x16x32_bf16 v[120:123], v[164:167], v[194:197], v[120:123]
	v_mfma_f32_16x16x32_bf16 v[108:111], v[136:139], v[202:205], v[108:111]
	v_mfma_f32_16x16x32_bf16 v[104:107], v[164:167], v[202:205], v[104:107]
	v_mfma_f32_16x16x32_bf16 v[92:95], v[136:139], v[210:213], v[92:95]
	v_mfma_f32_16x16x32_bf16 v[88:91], v[164:167], v[210:213], v[88:91]
	v_mfma_f32_16x16x32_bf16 v[76:79], v[136:139], v[218:221], v[76:79]
	v_mfma_f32_16x16x32_bf16 v[72:75], v[164:167], v[218:221], v[72:75]
	s_setprio 0
	s_setprio 1
	v_mfma_f32_16x16x32_bf16 v[116:119], v[174:177], v[190:193], v[116:119]
	v_mfma_f32_16x16x32_bf16 v[112:115], v[182:185], v[190:193], v[112:115]
	v_mfma_f32_16x16x32_bf16 v[100:103], v[174:177], v[198:201], v[100:103]
	v_mfma_f32_16x16x32_bf16 v[96:99], v[182:185], v[198:201], v[96:99]
	v_mfma_f32_16x16x32_bf16 v[84:87], v[174:177], v[206:209], v[84:87]
	v_mfma_f32_16x16x32_bf16 v[80:83], v[182:185], v[206:209], v[80:83]
	v_mfma_f32_16x16x32_bf16 v[68:71], v[174:177], v[214:217], v[68:71]
	v_mfma_f32_16x16x32_bf16 v[64:67], v[182:185], v[214:217], v[64:67]
	v_mfma_f32_16x16x32_bf16 v[116:119], v[178:181], v[194:197], v[116:119]
	v_mfma_f32_16x16x32_bf16 v[112:115], v[186:189], v[194:197], v[112:115]
	v_mfma_f32_16x16x32_bf16 v[100:103], v[178:181], v[202:205], v[100:103]
	v_mfma_f32_16x16x32_bf16 v[96:99], v[186:189], v[202:205], v[96:99]
	v_mfma_f32_16x16x32_bf16 v[84:87], v[178:181], v[210:213], v[84:87]
	v_mfma_f32_16x16x32_bf16 v[80:83], v[186:189], v[210:213], v[80:83]
	v_mfma_f32_16x16x32_bf16 v[68:71], v[178:181], v[218:221], v[68:71]
	v_mfma_f32_16x16x32_bf16 v[64:67], v[186:189], v[218:221], v[64:67]
	s_setprio 0
	s_barrier
	s_add_i32 s10, s72, s58
	s_mov_b32 m0, s10
	ds_read_b128 v[190:193], v172 offset:16384
	ds_read_b128 v[194:197], v172 offset:17408
	ds_read_b128 v[198:201], v172 offset:18432
	ds_read_b128 v[202:205], v172 offset:19456
	ds_read_b128 v[206:209], v172 offset:20480
	ds_read_b128 v[210:213], v172 offset:21504
	ds_read_b128 v[214:217], v172 offset:22528
	ds_read_b128 v[218:221], v172 offset:23552
	global_load_lds_dwordx4 v146, s[54:55]
	s_add_i32 m0, s10, 0x2000
	s_nop 0
	global_load_lds_dwordx4 v150, s[54:55]
	s_add_u32 s54, s54, 0x40000
	s_addc_u32 s55, s55, 0
	s_add_i32 s10, s73, s58
	s_mov_b32 m0, s10
	s_nop 0
	global_load_lds_dwordx4 v146, s[54:55]
	s_add_i32 m0, s10, 0x2000
	s_nop 0
	global_load_lds_dwordx4 v150, s[54:55]
	s_mov_b32 m0, s59
	s_nop 0
	global_load_lds_dwordx4 v144, s[56:57]
	s_mov_b32 m0, s60
	s_nop 0
	global_load_lds_dwordx4 v148, s[56:57]
	s_waitcnt vmcnt(8)
	s_waitcnt lgkmcnt(0)
	s_barrier
	s_setprio 1
	s_waitcnt lgkmcnt(0)
	v_mfma_f32_16x16x32_bf16 v[60:63], v[132:135], v[190:193], v[60:63]
	v_mfma_f32_16x16x32_bf16 v[56:59], v[140:143], v[190:193], v[56:59]
	v_mfma_f32_16x16x32_bf16 v[44:47], v[132:135], v[198:201], v[44:47]
	v_mfma_f32_16x16x32_bf16 v[40:43], v[140:143], v[198:201], v[40:43]
	v_mfma_f32_16x16x32_bf16 v[28:31], v[132:135], v[206:209], v[28:31]
	v_mfma_f32_16x16x32_bf16 v[24:27], v[140:143], v[206:209], v[24:27]
	v_mfma_f32_16x16x32_bf16 v[12:15], v[132:135], v[214:217], v[12:15]
	v_mfma_f32_16x16x32_bf16 v[8:11], v[140:143], v[214:217], v[8:11]
	v_mfma_f32_16x16x32_bf16 v[60:63], v[136:139], v[194:197], v[60:63]
	v_mfma_f32_16x16x32_bf16 v[56:59], v[164:167], v[194:197], v[56:59]
	v_mfma_f32_16x16x32_bf16 v[44:47], v[136:139], v[202:205], v[44:47]
	v_mfma_f32_16x16x32_bf16 v[40:43], v[164:167], v[202:205], v[40:43]
	v_mfma_f32_16x16x32_bf16 v[28:31], v[136:139], v[210:213], v[28:31]
	v_mfma_f32_16x16x32_bf16 v[24:27], v[164:167], v[210:213], v[24:27]
	v_mfma_f32_16x16x32_bf16 v[12:15], v[136:139], v[218:221], v[12:15]
	v_mfma_f32_16x16x32_bf16 v[8:11], v[164:167], v[218:221], v[8:11]
	s_setprio 0
	s_setprio 1
	v_mfma_f32_16x16x32_bf16 v[52:55], v[174:177], v[190:193], v[52:55]
	v_mfma_f32_16x16x32_bf16 v[48:51], v[182:185], v[190:193], v[48:51]
	v_mfma_f32_16x16x32_bf16 v[36:39], v[174:177], v[198:201], v[36:39]
	v_mfma_f32_16x16x32_bf16 v[32:35], v[182:185], v[198:201], v[32:35]
	v_mfma_f32_16x16x32_bf16 v[20:23], v[174:177], v[206:209], v[20:23]
	v_mfma_f32_16x16x32_bf16 v[16:19], v[182:185], v[206:209], v[16:19]
	v_mfma_f32_16x16x32_bf16 v[4:7], v[174:177], v[214:217], v[4:7]
	v_mfma_f32_16x16x32_bf16 v[0:3], v[182:185], v[214:217], v[0:3]
	v_mfma_f32_16x16x32_bf16 v[52:55], v[178:181], v[194:197], v[52:55]
	v_mfma_f32_16x16x32_bf16 v[48:51], v[186:189], v[194:197], v[48:51]
	v_mfma_f32_16x16x32_bf16 v[36:39], v[178:181], v[202:205], v[36:39]
	v_mfma_f32_16x16x32_bf16 v[32:35], v[186:189], v[202:205], v[32:35]
	v_mfma_f32_16x16x32_bf16 v[20:23], v[178:181], v[210:213], v[20:23]
	v_mfma_f32_16x16x32_bf16 v[16:19], v[186:189], v[210:213], v[16:19]
	v_mfma_f32_16x16x32_bf16 v[4:7], v[178:181], v[218:221], v[4:7]
	v_mfma_f32_16x16x32_bf16 v[0:3], v[186:189], v[218:221], v[0:3]
	s_setprio 0
	s_barrier
	s_add_i32 s10, 0, 0x18000
	s_add_i32 s83, 0, 0x1c000
	v_add_u32_e32 v164, s10, v171
	v_add_u32_e32 v168, s83, v171
	ds_read_b128 v[132:135], v164
	ds_read_b128 v[136:139], v164 offset:1024
	ds_read_b128 v[140:143], v164 offset:2048
	ds_read_b128 v[164:167], v164 offset:3072
	ds_read_b128 v[174:177], v168
	ds_read_b128 v[178:181], v168 offset:1024
	ds_read_b128 v[182:185], v168 offset:2048
	ds_read_b128 v[186:189], v168 offset:3072
	s_add_u32 s54, s56, 0x40000
	s_addc_u32 s55, s57, 0
	s_mov_b32 m0, s61
	ds_read_b128 v[190:193], v172 offset:32768
	ds_read_b128 v[194:197], v172 offset:33792
	ds_read_b128 v[198:201], v172 offset:34816
	ds_read_b128 v[202:205], v172 offset:35840
	ds_read_b128 v[206:209], v172 offset:36864
	ds_read_b128 v[210:213], v172 offset:37888
	ds_read_b128 v[214:217], v172 offset:38912
	ds_read_b128 v[218:221], v172 offset:39936
	global_load_lds_dwordx4 v144, s[54:55]
	s_mov_b32 m0, s62
	s_nop 0
	global_load_lds_dwordx4 v148, s[54:55]
	s_waitcnt vmcnt(8)
	s_waitcnt lgkmcnt(0)
	s_barrier
	s_setprio 1
	s_waitcnt lgkmcnt(0)
	v_mfma_f32_16x16x32_bf16 v[124:127], v[132:135], v[190:193], v[124:127]
	v_mfma_f32_16x16x32_bf16 v[120:123], v[140:143], v[190:193], v[120:123]
	v_mfma_f32_16x16x32_bf16 v[108:111], v[132:135], v[198:201], v[108:111]
	v_mfma_f32_16x16x32_bf16 v[104:107], v[140:143], v[198:201], v[104:107]
	v_mfma_f32_16x16x32_bf16 v[92:95], v[132:135], v[206:209], v[92:95]
	v_mfma_f32_16x16x32_bf16 v[88:91], v[140:143], v[206:209], v[88:91]
	v_mfma_f32_16x16x32_bf16 v[76:79], v[132:135], v[214:217], v[76:79]
	v_mfma_f32_16x16x32_bf16 v[72:75], v[140:143], v[214:217], v[72:75]
	v_mfma_f32_16x16x32_bf16 v[124:127], v[136:139], v[194:197], v[124:127]
	v_mfma_f32_16x16x32_bf16 v[120:123], v[164:167], v[194:197], v[120:123]
	v_mfma_f32_16x16x32_bf16 v[108:111], v[136:139], v[202:205], v[108:111]
	v_mfma_f32_16x16x32_bf16 v[104:107], v[164:167], v[202:205], v[104:107]
	v_mfma_f32_16x16x32_bf16 v[92:95], v[136:139], v[210:213], v[92:95]
	v_mfma_f32_16x16x32_bf16 v[88:91], v[164:167], v[210:213], v[88:91]
	v_mfma_f32_16x16x32_bf16 v[76:79], v[136:139], v[218:221], v[76:79]
	v_mfma_f32_16x16x32_bf16 v[72:75], v[164:167], v[218:221], v[72:75]
	s_setprio 0
	s_setprio 1
	v_mfma_f32_16x16x32_bf16 v[116:119], v[174:177], v[190:193], v[116:119]
	v_mfma_f32_16x16x32_bf16 v[112:115], v[182:185], v[190:193], v[112:115]
	v_mfma_f32_16x16x32_bf16 v[100:103], v[174:177], v[198:201], v[100:103]
	v_mfma_f32_16x16x32_bf16 v[96:99], v[182:185], v[198:201], v[96:99]
	v_mfma_f32_16x16x32_bf16 v[84:87], v[174:177], v[206:209], v[84:87]
	v_mfma_f32_16x16x32_bf16 v[80:83], v[182:185], v[206:209], v[80:83]
	v_mfma_f32_16x16x32_bf16 v[68:71], v[174:177], v[214:217], v[68:71]
	v_mfma_f32_16x16x32_bf16 v[64:67], v[182:185], v[214:217], v[64:67]
	v_mfma_f32_16x16x32_bf16 v[116:119], v[178:181], v[194:197], v[116:119]
	v_mfma_f32_16x16x32_bf16 v[112:115], v[186:189], v[194:197], v[112:115]
	v_mfma_f32_16x16x32_bf16 v[100:103], v[178:181], v[202:205], v[100:103]
	v_mfma_f32_16x16x32_bf16 v[96:99], v[186:189], v[202:205], v[96:99]
	v_mfma_f32_16x16x32_bf16 v[84:87], v[178:181], v[210:213], v[84:87]
	v_mfma_f32_16x16x32_bf16 v[80:83], v[186:189], v[210:213], v[80:83]
	v_mfma_f32_16x16x32_bf16 v[68:71], v[178:181], v[218:221], v[68:71]
	v_mfma_f32_16x16x32_bf16 v[64:67], v[186:189], v[218:221], v[64:67]
	s_setprio 0
	s_barrier
	s_add_i32 s10, s10, s58
	s_mov_b32 m0, s10
	ds_read_b128 v[190:193], v172 offset:49152
	ds_read_b128 v[194:197], v172 offset:50176
	ds_read_b128 v[198:201], v172 offset:51200
	ds_read_b128 v[202:205], v172 offset:52224
	ds_read_b128 v[206:209], v172 offset:53248
	ds_read_b128 v[210:213], v172 offset:54272
	ds_read_b128 v[214:217], v172 offset:55296
	ds_read_b128 v[218:221], v172 offset:56320
	global_load_lds_dwordx4 v146, s[52:53]
	s_add_i32 m0, s10, 0x2000
	s_nop 0
	global_load_lds_dwordx4 v150, s[52:53]
	s_add_u32 s52, s52, 0x40000
	s_addc_u32 s53, s53, 0
	s_add_i32 s10, s83, s58
	s_mov_b32 m0, s10
	s_nop 0
	global_load_lds_dwordx4 v146, s[52:53]
	s_add_i32 m0, s10, 0x2000
	s_nop 0
	global_load_lds_dwordx4 v150, s[52:53]
	s_mov_b32 m0, s68
	s_nop 0
	global_load_lds_dwordx4 v144, s[50:51]
	s_mov_b32 m0, s69
	s_nop 0
	global_load_lds_dwordx4 v148, s[50:51]
	s_waitcnt vmcnt(8)
	s_waitcnt lgkmcnt(0)
	s_barrier
	s_setprio 1
	s_waitcnt lgkmcnt(0)
	v_mfma_f32_16x16x32_bf16 v[60:63], v[132:135], v[190:193], v[60:63]
	v_mfma_f32_16x16x32_bf16 v[56:59], v[140:143], v[190:193], v[56:59]
	v_mfma_f32_16x16x32_bf16 v[44:47], v[132:135], v[198:201], v[44:47]
	v_mfma_f32_16x16x32_bf16 v[40:43], v[140:143], v[198:201], v[40:43]
	v_mfma_f32_16x16x32_bf16 v[28:31], v[132:135], v[206:209], v[28:31]
	v_mfma_f32_16x16x32_bf16 v[24:27], v[140:143], v[206:209], v[24:27]
	v_mfma_f32_16x16x32_bf16 v[12:15], v[132:135], v[214:217], v[12:15]
	v_mfma_f32_16x16x32_bf16 v[8:11], v[140:143], v[214:217], v[8:11]
	v_mfma_f32_16x16x32_bf16 v[60:63], v[136:139], v[194:197], v[60:63]
	v_mfma_f32_16x16x32_bf16 v[56:59], v[164:167], v[194:197], v[56:59]
	v_mfma_f32_16x16x32_bf16 v[44:47], v[136:139], v[202:205], v[44:47]
	v_mfma_f32_16x16x32_bf16 v[40:43], v[164:167], v[202:205], v[40:43]
	v_mfma_f32_16x16x32_bf16 v[28:31], v[136:139], v[210:213], v[28:31]
	v_mfma_f32_16x16x32_bf16 v[24:27], v[164:167], v[210:213], v[24:27]
	v_mfma_f32_16x16x32_bf16 v[12:15], v[136:139], v[218:221], v[12:15]
	v_mfma_f32_16x16x32_bf16 v[8:11], v[164:167], v[218:221], v[8:11]
	s_setprio 0
	s_setprio 1
	v_mfma_f32_16x16x32_bf16 v[52:55], v[174:177], v[190:193], v[52:55]
	v_mfma_f32_16x16x32_bf16 v[48:51], v[182:185], v[190:193], v[48:51]
	v_mfma_f32_16x16x32_bf16 v[36:39], v[174:177], v[198:201], v[36:39]
	v_mfma_f32_16x16x32_bf16 v[32:35], v[182:185], v[198:201], v[32:35]
	v_mfma_f32_16x16x32_bf16 v[20:23], v[174:177], v[206:209], v[20:23]
	v_mfma_f32_16x16x32_bf16 v[16:19], v[182:185], v[206:209], v[16:19]
	v_mfma_f32_16x16x32_bf16 v[4:7], v[174:177], v[214:217], v[4:7]
	v_mfma_f32_16x16x32_bf16 v[0:3], v[182:185], v[214:217], v[0:3]
	v_mfma_f32_16x16x32_bf16 v[52:55], v[178:181], v[194:197], v[52:55]
	v_mfma_f32_16x16x32_bf16 v[48:51], v[186:189], v[194:197], v[48:51]
	v_mfma_f32_16x16x32_bf16 v[36:39], v[178:181], v[202:205], v[36:39]
	v_mfma_f32_16x16x32_bf16 v[32:35], v[186:189], v[202:205], v[32:35]
	v_mfma_f32_16x16x32_bf16 v[20:23], v[178:181], v[210:213], v[20:23]
	v_mfma_f32_16x16x32_bf16 v[16:19], v[186:189], v[210:213], v[16:19]
	v_mfma_f32_16x16x32_bf16 v[4:7], v[178:181], v[218:221], v[4:7]
	v_mfma_f32_16x16x32_bf16 v[0:3], v[186:189], v[218:221], v[0:3]
	s_setprio 0
	s_barrier
	s_add_i32 s10, s82, 2
	s_add_u32 s48, s48, 0x100
	s_addc_u32 s49, s49, 0
	s_cmp_gt_u32 s82, 13
	s_mov_b32 s82, s10
	s_cbranch_scc1 .LBB0_721

.LBB0_800:
	s_add_u32 s61, s76, 0x7c00800
	s_addc_u32 s62, s77, 0
	s_add_u32 s63, s76, 0x1000800
	s_addc_u32 s64, s77, 0
	s_add_u32 s12, s76, 0xbc00000
	s_addc_u32 s13, s77, 0
	s_lshl_b32 s14, s14, 5
	s_and_b32 s20, s14, 0x60
	s_mov_b64 s[14:15], 0x80
	s_add_i32 m0, s57, 0x18000
	v_lshl_add_u64 v[6:7], v[6:7], 0, s[14:15]
	s_waitcnt vmcnt(2)
	s_barrier
	global_load_lds_dwordx4 v[6:7], off
	v_lshl_add_u64 v[4:5], v[4:5], 0, s[14:15]
	s_add_i32 m0, s57, 0x1a000
	s_add_i32 s65, s57, 0x8000
	s_lshl_b32 s16, s8, 13
	s_lshl_b32 s18, s20, 7
	global_load_lds_dwordx4 v[4:5], off
	v_lshl_add_u64 v[0:1], v[0:1], 0, s[14:15]
	s_mov_b32 m0, s65
	s_add_i32 s66, s57, 0xa000
	global_load_lds_dwordx4 v[0:1], off
	v_lshl_add_u64 v[0:1], v[2:3], 0, s[14:15]
	s_add_u32 s14, s28, 0x40080
	s_mov_b32 m0, s66
	s_addc_u32 s15, s29, 0
	global_load_lds_dwordx4 v[0:1], off
	s_add_i32 m0, s57, 0x1c000
	s_nop 0
	global_load_lds_dwordx4 v128, s[14:15]
	s_add_i32 m0, s57, 0x1e000
	v_and_b32_e32 v2, 15, v10
	global_load_lds_dwordx4 v130, s[14:15]
	v_bfe_u32 v1, v10, 4, 2
	v_lshlrev_b32_e32 v136, 4, v1
	v_lshl_or_b32 v153, s8, 6, v2
	v_lshlrev_b32_e32 v0, 3, v1
	v_lshl_or_b32 v1, v2, 6, v136
	v_lshlrev_b32_e32 v2, 2, v10
	v_and_b32_e32 v2, 32, v2
	v_bitop3_b32 v4, v1, s16, v2 bitop3:0xde
	v_bitop3_b32 v157, v1, s18, v2 bitop3:0xde
	v_mov_b32_e32 v137, 0
	v_lshlrev_b32_e32 v1, 14, v13
	s_sext_i32_i8 s17, s0
	s_cmpk_lt_u32 s1, 0x100
	v_lshl_add_u64 v[2:3], s[76:77], 0, v[136:137]
	s_mov_b64 s[0:1], 0x2800000
	v_and_b32_e32 v1, 0xffff8000, v1
	v_lshl_add_u64 v[138:139], v[2:3], 0, s[0:1]
	v_lshl_add_u32 v1, v12, 11, v1
	v_and_b32_e32 v2, 1, v13
	v_lshl_or_b32 v1, v2, 6, v1
	v_lshl_add_u32 v136, v14, 1, v1
	v_lshlrev_b32_e32 v1, 14, v8
	v_and_b32_e32 v1, 0xffff8000, v1
	v_lshl_add_u32 v1, v9, 11, v1
	v_and_b32_e32 v2, 1, v8
	s_mov_b64 s[18:19], 0x40080
	s_waitcnt vmcnt(6)
	v_lshl_or_b32 v1, v2, 6, v1
	v_lshl_add_u64 v[140:141], v[136:137], 0, s[18:19]
	v_lshl_add_u32 v136, v11, 1, v1
	s_cselect_b64 s[14:15], -1, 0
	s_ashr_i32 s67, s3, 31
	v_lshl_add_u64 v[142:143], v[136:137], 0, s[18:19]
	v_mov_b64_e32 v[144:145], 0xb00
	v_mov_b64_e32 v[146:147], 0xaff
	s_add_i32 s68, 0, 0x10000
	s_add_i32 s69, 0, 0x14000
	v_add_u32_e32 v161, 0, v4
	v_mov_b32_e32 v165, 0x358637bd
	s_movk_i32 s70, 0x1600
	s_lshl_b32 s16, s20, 1
	v_lshlrev_b32_e32 v136, 1, v0
	s_mov_b32 s71, 0
	s_barrier
	s_branch .LBB0_803

.LBB0_806:
	v_add_u32_e32 v152, s68, v157
	ds_read_b128 v[166:169], v152
	ds_read_b128 v[170:173], v152 offset:1024
	ds_read_b128 v[174:177], v152 offset:2048
	ds_read_b128 v[178:181], v152 offset:3072
	v_add_u32_e32 v152, s69, v157
	ds_read_b128 v[182:185], v152
	ds_read_b128 v[186:189], v152 offset:1024
	ds_read_b128 v[190:193], v152 offset:2048
	ds_read_b128 v[194:197], v152 offset:3072
	s_add_u32 s8, s52, 0x100
	s_addc_u32 s84, s53, 0
	s_and_b64 s[52:53], exec, s[50:51]
	s_cselect_b32 s53, s21, s84
	s_cselect_b32 s52, s79, s8
	s_add_u32 s8, s83, 0x100
	s_addc_u32 s82, s82, 0
	s_and_b64 s[50:51], exec, s[50:51]
	s_cselect_b32 s51, s19, s82
	s_cselect_b32 s50, s80, s8
	v_lshl_add_u64 v[154:155], v[148:149], 0, s[44:45]
	s_add_i32 m0, s57, 0xc000
	ds_read_b128 v[198:201], v161
	ds_read_b128 v[202:205], v161 offset:1024
	ds_read_b128 v[206:209], v161 offset:2048
	ds_read_b128 v[210:213], v161 offset:3072
	ds_read_b128 v[214:217], v161 offset:4096
	ds_read_b128 v[218:221], v161 offset:5120
	ds_read_b128 v[222:225], v161 offset:6144
	ds_read_b128 v[226:229], v161 offset:7168
	global_load_lds_dwordx4 v[154:155], off
	v_lshl_add_u64 v[154:155], v[150:151], 0, s[44:45]
	s_add_i32 m0, s57, 0xe000
	s_nop 0
	global_load_lds_dwordx4 v[154:155], off
	s_waitcnt vmcnt(8)
	s_waitcnt lgkmcnt(0)
	s_barrier
	s_setprio 1
	s_waitcnt lgkmcnt(0)
	v_mfma_f32_16x16x32_bf16 v[124:127], v[166:169], v[198:201], v[124:127]
	v_mfma_f32_16x16x32_bf16 v[120:123], v[174:177], v[198:201], v[120:123]
	v_mfma_f32_16x16x32_bf16 v[108:111], v[166:169], v[206:209], v[108:111]
	v_mfma_f32_16x16x32_bf16 v[104:107], v[174:177], v[206:209], v[104:107]
	v_mfma_f32_16x16x32_bf16 v[92:95], v[166:169], v[214:217], v[92:95]
	v_mfma_f32_16x16x32_bf16 v[88:91], v[174:177], v[214:217], v[88:91]
	v_mfma_f32_16x16x32_bf16 v[76:79], v[166:169], v[222:225], v[76:79]
	v_mfma_f32_16x16x32_bf16 v[72:75], v[174:177], v[222:225], v[72:75]
	v_mfma_f32_16x16x32_bf16 v[124:127], v[170:173], v[202:205], v[124:127]
	v_mfma_f32_16x16x32_bf16 v[120:123], v[178:181], v[202:205], v[120:123]
	v_mfma_f32_16x16x32_bf16 v[108:111], v[170:173], v[210:213], v[108:111]
	v_mfma_f32_16x16x32_bf16 v[104:107], v[178:181], v[210:213], v[104:107]
	v_mfma_f32_16x16x32_bf16 v[92:95], v[170:173], v[218:221], v[92:95]
	v_mfma_f32_16x16x32_bf16 v[88:91], v[178:181], v[218:221], v[88:91]
	v_mfma_f32_16x16x32_bf16 v[76:79], v[170:173], v[226:229], v[76:79]
	v_mfma_f32_16x16x32_bf16 v[72:75], v[178:181], v[226:229], v[72:75]
	s_setprio 0
	s_setprio 1
	v_mfma_f32_16x16x32_bf16 v[116:119], v[182:185], v[198:201], v[116:119]
	v_mfma_f32_16x16x32_bf16 v[112:115], v[190:193], v[198:201], v[112:115]
	v_mfma_f32_16x16x32_bf16 v[100:103], v[182:185], v[206:209], v[100:103]
	v_mfma_f32_16x16x32_bf16 v[96:99], v[190:193], v[206:209], v[96:99]
	v_mfma_f32_16x16x32_bf16 v[84:87], v[182:185], v[214:217], v[84:87]
	v_mfma_f32_16x16x32_bf16 v[80:83], v[190:193], v[214:217], v[80:83]
	v_mfma_f32_16x16x32_bf16 v[68:71], v[182:185], v[222:225], v[68:71]
	v_mfma_f32_16x16x32_bf16 v[64:67], v[190:193], v[222:225], v[64:67]
	v_mfma_f32_16x16x32_bf16 v[116:119], v[186:189], v[202:205], v[116:119]
	v_mfma_f32_16x16x32_bf16 v[112:115], v[194:197], v[202:205], v[112:115]
	v_mfma_f32_16x16x32_bf16 v[100:103], v[186:189], v[210:213], v[100:103]
	v_mfma_f32_16x16x32_bf16 v[96:99], v[194:197], v[210:213], v[96:99]
	v_mfma_f32_16x16x32_bf16 v[84:87], v[186:189], v[218:221], v[84:87]
	v_mfma_f32_16x16x32_bf16 v[80:83], v[194:197], v[218:221], v[80:83]
	v_mfma_f32_16x16x32_bf16 v[68:71], v[186:189], v[226:229], v[68:71]
	v_mfma_f32_16x16x32_bf16 v[64:67], v[194:197], v[226:229], v[64:67]
	s_setprio 0
	s_barrier
	s_add_i32 s8, s68, s54
	s_mov_b32 m0, s8
	ds_read_b128 v[198:201], v161 offset:16384
	ds_read_b128 v[202:205], v161 offset:17408
	ds_read_b128 v[206:209], v161 offset:18432
	ds_read_b128 v[210:213], v161 offset:19456
	ds_read_b128 v[214:217], v161 offset:20480
	ds_read_b128 v[218:221], v161 offset:21504
	ds_read_b128 v[222:225], v161 offset:22528
	ds_read_b128 v[226:229], v161 offset:23552
	global_load_lds_dwordx4 v128, s[50:51]
	s_add_i32 m0, s8, 0x2000
	s_nop 0
	global_load_lds_dwordx4 v130, s[50:51]
	s_add_u32 s50, s50, 0x40000
	s_addc_u32 s51, s51, 0
	s_add_i32 s8, s69, s54
	s_mov_b32 m0, s8
	s_nop 0
	global_load_lds_dwordx4 v128, s[50:51]
	s_add_i32 m0, s8, 0x2000
	s_nop 0
	global_load_lds_dwordx4 v130, s[50:51]
	s_mov_b32 m0, s57
	s_nop 0
	global_load_lds_dwordx4 v134, s[52:53]
	s_mov_b32 m0, s58
	s_nop 0
	global_load_lds_dwordx4 v132, s[52:53]
	s_waitcnt vmcnt(8)
	s_waitcnt lgkmcnt(0)
	s_barrier
	s_setprio 1
	s_waitcnt lgkmcnt(0)
	v_mfma_f32_16x16x32_bf16 v[60:63], v[166:169], v[198:201], v[60:63]
	v_mfma_f32_16x16x32_bf16 v[56:59], v[174:177], v[198:201], v[56:59]
	v_mfma_f32_16x16x32_bf16 v[44:47], v[166:169], v[206:209], v[44:47]
	v_mfma_f32_16x16x32_bf16 v[40:43], v[174:177], v[206:209], v[40:43]
	v_mfma_f32_16x16x32_bf16 v[28:31], v[166:169], v[214:217], v[28:31]
	v_mfma_f32_16x16x32_bf16 v[24:27], v[174:177], v[214:217], v[24:27]
	v_mfma_f32_16x16x32_bf16 v[12:15], v[166:169], v[222:225], v[12:15]
	v_mfma_f32_16x16x32_bf16 v[8:11], v[174:177], v[222:225], v[8:11]
	v_mfma_f32_16x16x32_bf16 v[60:63], v[170:173], v[202:205], v[60:63]
	v_mfma_f32_16x16x32_bf16 v[56:59], v[178:181], v[202:205], v[56:59]
	v_mfma_f32_16x16x32_bf16 v[44:47], v[170:173], v[210:213], v[44:47]
	v_mfma_f32_16x16x32_bf16 v[40:43], v[178:181], v[210:213], v[40:43]
	v_mfma_f32_16x16x32_bf16 v[28:31], v[170:173], v[218:221], v[28:31]
	v_mfma_f32_16x16x32_bf16 v[24:27], v[178:181], v[218:221], v[24:27]
	v_mfma_f32_16x16x32_bf16 v[12:15], v[170:173], v[226:229], v[12:15]
	v_mfma_f32_16x16x32_bf16 v[8:11], v[178:181], v[226:229], v[8:11]
	s_setprio 0
	s_setprio 1
	v_mfma_f32_16x16x32_bf16 v[52:55], v[182:185], v[198:201], v[52:55]
	v_mfma_f32_16x16x32_bf16 v[48:51], v[190:193], v[198:201], v[48:51]
	v_mfma_f32_16x16x32_bf16 v[36:39], v[182:185], v[206:209], v[36:39]
	v_mfma_f32_16x16x32_bf16 v[32:35], v[190:193], v[206:209], v[32:35]
	v_mfma_f32_16x16x32_bf16 v[20:23], v[182:185], v[214:217], v[20:23]
	v_mfma_f32_16x16x32_bf16 v[16:19], v[190:193], v[214:217], v[16:19]
	v_mfma_f32_16x16x32_bf16 v[4:7], v[182:185], v[222:225], v[4:7]
	v_mfma_f32_16x16x32_bf16 v[0:3], v[190:193], v[222:225], v[0:3]
	v_mfma_f32_16x16x32_bf16 v[52:55], v[186:189], v[202:205], v[52:55]
	v_mfma_f32_16x16x32_bf16 v[48:51], v[194:197], v[202:205], v[48:51]
	v_mfma_f32_16x16x32_bf16 v[36:39], v[186:189], v[210:213], v[36:39]
	v_mfma_f32_16x16x32_bf16 v[32:35], v[194:197], v[210:213], v[32:35]
	v_mfma_f32_16x16x32_bf16 v[20:23], v[186:189], v[218:221], v[20:23]
	v_mfma_f32_16x16x32_bf16 v[16:19], v[194:197], v[218:221], v[16:19]
	v_mfma_f32_16x16x32_bf16 v[4:7], v[186:189], v[226:229], v[4:7]
	v_mfma_f32_16x16x32_bf16 v[0:3], v[194:197], v[226:229], v[0:3]
	s_setprio 0
	s_barrier
	s_add_i32 s8, 0, 0x18000
	v_add_u32_e32 v152, s8, v157
	s_add_i32 s82, 0, 0x1c000
	ds_read_b128 v[166:169], v152
	ds_read_b128 v[170:173], v152 offset:1024
	ds_read_b128 v[174:177], v152 offset:2048
	ds_read_b128 v[178:181], v152 offset:3072
	v_add_u32_e32 v152, s82, v157
	ds_read_b128 v[182:185], v152
	ds_read_b128 v[186:189], v152 offset:1024
	ds_read_b128 v[190:193], v152 offset:2048
	ds_read_b128 v[194:197], v152 offset:3072
	s_add_u32 s50, s52, 0x40000
	s_addc_u32 s51, s53, 0
	s_mov_b32 m0, s59
	ds_read_b128 v[198:201], v161 offset:32768
	ds_read_b128 v[202:205], v161 offset:33792
	ds_read_b128 v[206:209], v161 offset:34816
	ds_read_b128 v[210:213], v161 offset:35840
	ds_read_b128 v[214:217], v161 offset:36864
	ds_read_b128 v[218:221], v161 offset:37888
	ds_read_b128 v[222:225], v161 offset:38912
	ds_read_b128 v[226:229], v161 offset:39936
	global_load_lds_dwordx4 v134, s[50:51]
	s_mov_b32 m0, s60
	s_nop 0
	global_load_lds_dwordx4 v132, s[50:51]
	s_waitcnt vmcnt(8)
	s_waitcnt lgkmcnt(0)
	s_barrier
	s_setprio 1
	s_waitcnt lgkmcnt(0)
	v_mfma_f32_16x16x32_bf16 v[124:127], v[166:169], v[198:201], v[124:127]
	v_mfma_f32_16x16x32_bf16 v[120:123], v[174:177], v[198:201], v[120:123]
	v_mfma_f32_16x16x32_bf16 v[108:111], v[166:169], v[206:209], v[108:111]
	v_mfma_f32_16x16x32_bf16 v[104:107], v[174:177], v[206:209], v[104:107]
	v_mfma_f32_16x16x32_bf16 v[92:95], v[166:169], v[214:217], v[92:95]
	v_mfma_f32_16x16x32_bf16 v[88:91], v[174:177], v[214:217], v[88:91]
	v_mfma_f32_16x16x32_bf16 v[76:79], v[166:169], v[222:225], v[76:79]
	v_mfma_f32_16x16x32_bf16 v[72:75], v[174:177], v[222:225], v[72:75]
	v_mfma_f32_16x16x32_bf16 v[124:127], v[170:173], v[202:205], v[124:127]
	v_mfma_f32_16x16x32_bf16 v[120:123], v[178:181], v[202:205], v[120:123]
	v_mfma_f32_16x16x32_bf16 v[108:111], v[170:173], v[210:213], v[108:111]
	v_mfma_f32_16x16x32_bf16 v[104:107], v[178:181], v[210:213], v[104:107]
	v_mfma_f32_16x16x32_bf16 v[92:95], v[170:173], v[218:221], v[92:95]
	v_mfma_f32_16x16x32_bf16 v[88:91], v[178:181], v[218:221], v[88:91]
	v_mfma_f32_16x16x32_bf16 v[76:79], v[170:173], v[226:229], v[76:79]
	v_mfma_f32_16x16x32_bf16 v[72:75], v[178:181], v[226:229], v[72:75]
	s_setprio 0
	s_setprio 1
	v_mfma_f32_16x16x32_bf16 v[116:119], v[182:185], v[198:201], v[116:119]
	v_mfma_f32_16x16x32_bf16 v[112:115], v[190:193], v[198:201], v[112:115]
	v_mfma_f32_16x16x32_bf16 v[100:103], v[182:185], v[206:209], v[100:103]
	v_mfma_f32_16x16x32_bf16 v[96:99], v[190:193], v[206:209], v[96:99]
	v_mfma_f32_16x16x32_bf16 v[84:87], v[182:185], v[214:217], v[84:87]
	v_mfma_f32_16x16x32_bf16 v[80:83], v[190:193], v[214:217], v[80:83]
	v_mfma_f32_16x16x32_bf16 v[68:71], v[182:185], v[222:225], v[68:71]
	v_mfma_f32_16x16x32_bf16 v[64:67], v[190:193], v[222:225], v[64:67]
	v_mfma_f32_16x16x32_bf16 v[116:119], v[186:189], v[202:205], v[116:119]
	v_mfma_f32_16x16x32_bf16 v[112:115], v[194:197], v[202:205], v[112:115]
	v_mfma_f32_16x16x32_bf16 v[100:103], v[186:189], v[210:213], v[100:103]
	v_mfma_f32_16x16x32_bf16 v[96:99], v[194:197], v[210:213], v[96:99]
	v_mfma_f32_16x16x32_bf16 v[84:87], v[186:189], v[218:221], v[84:87]
	v_mfma_f32_16x16x32_bf16 v[80:83], v[194:197], v[218:221], v[80:83]
	v_mfma_f32_16x16x32_bf16 v[68:71], v[186:189], v[226:229], v[68:71]
	v_mfma_f32_16x16x32_bf16 v[64:67], v[194:197], v[226:229], v[64:67]
	s_setprio 0
	s_barrier
	s_add_i32 s8, s8, s54
	s_mov_b32 m0, s8
	ds_read_b128 v[198:201], v161 offset:49152
	ds_read_b128 v[202:205], v161 offset:50176
	ds_read_b128 v[206:209], v161 offset:51200
	ds_read_b128 v[210:213], v161 offset:52224
	ds_read_b128 v[214:217], v161 offset:53248
	ds_read_b128 v[218:221], v161 offset:54272
	ds_read_b128 v[222:225], v161 offset:55296
	ds_read_b128 v[226:229], v161 offset:56320
	global_load_lds_dwordx4 v128, s[48:49]
	s_add_i32 m0, s8, 0x2000
	s_nop 0
	global_load_lds_dwordx4 v130, s[48:49]
	s_add_u32 s48, s48, 0x40000
	s_addc_u32 s49, s49, 0
	s_add_i32 s8, s82, s54
	s_mov_b32 m0, s8
	s_nop 0
	global_load_lds_dwordx4 v128, s[48:49]
	s_add_i32 m0, s8, 0x2000
	s_nop 0
	global_load_lds_dwordx4 v130, s[48:49]
	s_mov_b32 m0, s65
	s_nop 0
	global_load_lds_dwordx4 v134, s[46:47]
	s_mov_b32 m0, s66
	s_nop 0
	global_load_lds_dwordx4 v132, s[46:47]
	s_waitcnt vmcnt(8)
	s_waitcnt lgkmcnt(0)
	s_barrier
	s_setprio 1
	s_waitcnt lgkmcnt(0)
	v_mfma_f32_16x16x32_bf16 v[60:63], v[166:169], v[198:201], v[60:63]
	v_mfma_f32_16x16x32_bf16 v[56:59], v[174:177], v[198:201], v[56:59]
	v_mfma_f32_16x16x32_bf16 v[44:47], v[166:169], v[206:209], v[44:47]
	v_mfma_f32_16x16x32_bf16 v[40:43], v[174:177], v[206:209], v[40:43]
	v_mfma_f32_16x16x32_bf16 v[28:31], v[166:169], v[214:217], v[28:31]
	v_mfma_f32_16x16x32_bf16 v[24:27], v[174:177], v[214:217], v[24:27]
	v_mfma_f32_16x16x32_bf16 v[12:15], v[166:169], v[222:225], v[12:15]
	v_mfma_f32_16x16x32_bf16 v[8:11], v[174:177], v[222:225], v[8:11]
	v_mfma_f32_16x16x32_bf16 v[60:63], v[170:173], v[202:205], v[60:63]
	v_mfma_f32_16x16x32_bf16 v[56:59], v[178:181], v[202:205], v[56:59]
	v_mfma_f32_16x16x32_bf16 v[44:47], v[170:173], v[210:213], v[44:47]
	v_mfma_f32_16x16x32_bf16 v[40:43], v[178:181], v[210:213], v[40:43]
	v_mfma_f32_16x16x32_bf16 v[28:31], v[170:173], v[218:221], v[28:31]
	v_mfma_f32_16x16x32_bf16 v[24:27], v[178:181], v[218:221], v[24:27]
	v_mfma_f32_16x16x32_bf16 v[12:15], v[170:173], v[226:229], v[12:15]
	v_mfma_f32_16x16x32_bf16 v[8:11], v[178:181], v[226:229], v[8:11]
	s_setprio 0
	s_setprio 1
	v_mfma_f32_16x16x32_bf16 v[52:55], v[182:185], v[198:201], v[52:55]
	v_mfma_f32_16x16x32_bf16 v[48:51], v[190:193], v[198:201], v[48:51]
	v_mfma_f32_16x16x32_bf16 v[36:39], v[182:185], v[206:209], v[36:39]
	v_mfma_f32_16x16x32_bf16 v[32:35], v[190:193], v[206:209], v[32:35]
	v_mfma_f32_16x16x32_bf16 v[20:23], v[182:185], v[214:217], v[20:23]
	v_mfma_f32_16x16x32_bf16 v[16:19], v[190:193], v[214:217], v[16:19]
	v_mfma_f32_16x16x32_bf16 v[4:7], v[182:185], v[222:225], v[4:7]
	v_mfma_f32_16x16x32_bf16 v[0:3], v[190:193], v[222:225], v[0:3]
	v_mfma_f32_16x16x32_bf16 v[52:55], v[186:189], v[202:205], v[52:55]
	v_mfma_f32_16x16x32_bf16 v[48:51], v[194:197], v[202:205], v[48:51]
	v_mfma_f32_16x16x32_bf16 v[36:39], v[186:189], v[210:213], v[36:39]
	v_mfma_f32_16x16x32_bf16 v[32:35], v[194:197], v[210:213], v[32:35]
	v_mfma_f32_16x16x32_bf16 v[20:23], v[186:189], v[218:221], v[20:23]
	v_mfma_f32_16x16x32_bf16 v[16:19], v[194:197], v[218:221], v[16:19]
	v_mfma_f32_16x16x32_bf16 v[4:7], v[186:189], v[226:229], v[4:7]
	v_mfma_f32_16x16x32_bf16 v[0:3], v[194:197], v[226:229], v[0:3]
	s_setprio 0
	s_barrier
	s_add_i32 s8, s81, 2
	s_add_u32 s44, s44, 0x100
	s_addc_u32 s45, s45, 0
	s_cmp_gt_u32 s81, 13
	s_mov_b32 s81, s8
	s_cbranch_scc1 .LBB0_813

.LBB0_882:
	s_add_u32 s55, s76, 0xbc01600
	s_addc_u32 s56, s77, 0
	s_add_u32 s57, s76, 0x1b01600
	s_addc_u32 s58, s77, 0
	s_add_u32 s12, s76, 0x2a00000
	s_mov_b64 s[14:15], 0x80
	s_addc_u32 s13, s77, 0
	s_add_i32 m0, s51, 0x18000
	v_lshl_add_u64 v[6:7], v[6:7], 0, s[14:15]
	s_and_b32 s59, s0, 3
	s_waitcnt vmcnt(2)
	s_barrier
	global_load_lds_dwordx4 v[6:7], off
	v_lshl_add_u64 v[4:5], v[4:5], 0, s[14:15]
	s_add_i32 m0, s51, 0x1a000
	s_add_i32 s60, s51, 0x8000
	s_lshl_b32 s0, s1, 13
	s_lshl_b32 s8, s59, 5
	s_lshl_b32 s5, s59, 12
	global_load_lds_dwordx4 v[4:5], off
	v_lshl_add_u64 v[0:1], v[0:1], 0, s[14:15]
	s_mov_b32 m0, s60
	s_add_i32 s61, s51, 0xa000
	global_load_lds_dwordx4 v[0:1], off
	v_lshl_add_u64 v[0:1], v[2:3], 0, s[14:15]
	s_add_u32 s14, s24, 0xb0080
	s_mov_b32 m0, s61
	s_addc_u32 s15, s25, 0
	global_load_lds_dwordx4 v[0:1], off
	s_add_i32 m0, s51, 0x1c000
	s_nop 0
	global_load_lds_dwordx4 v138, s[14:15]
	s_add_i32 m0, s51, 0x1e000
	v_and_b32_e32 v2, 15, v8
	global_load_lds_dwordx4 v142, s[14:15]
	v_bfe_u32 v1, v8, 4, 2
	v_lshlrev_b32_e32 v144, 4, v1
	v_lshlrev_b32_e32 v3, 2, v8
	v_lshl_or_b32 v164, s1, 6, v2
	v_lshl_or_b32 v2, v2, 6, v144
	v_and_b32_e32 v3, 32, v3
	s_cmpk_lt_u32 s6, 0x100
	v_bitop3_b32 v165, v2, s5, v3 bitop3:0xde
	s_cselect_b64 s[14:15], -1, 0
	s_ashr_i32 s62, s3, 31
	s_ashr_i32 s63, s2, 31
	s_lshl_b32 s5, s59, 6
	s_add_u32 s6, s40, s5
	v_lshlrev_b32_e32 v0, 3, v1
	v_bitop3_b32 v4, v2, s0, v3 bitop3:0xde
	v_cmp_eq_u32_e64 s[0:1], 0, v1
	s_addc_u32 s7, s41, 0
	v_lshrrev_b32_e32 v1, 1, v9
	v_mul_lo_u32 v2, v11, s4
	s_mov_b32 s5, 0xb000
	v_lshl_add_u64 v[146:147], s[6:7], 0, v[144:145]
	v_mad_u64_u32 v[2:3], s[6:7], v1, s5, v[2:3]
	v_or_b32_e32 v1, v2, v10
	v_add_lshl_u32 v144, v1, v12, 1
	v_lshrrev_b32_e32 v1, 1, v13
	v_mul_lo_u32 v2, v14, s4
	v_mad_u64_u32 v[2:3], s[4:5], v1, s5, v[2:3]
	s_mov_b64 s[18:19], 0xb0080
	s_waitcnt vmcnt(6)
	v_or_b32_e32 v1, v2, v15
	v_lshl_add_u64 v[148:149], v[144:145], 0, s[18:19]
	v_add_lshl_u32 v144, v1, v16, 1
	v_lshl_add_u64 v[150:151], v[144:145], 0, s[18:19]
	v_mov_b64_e32 v[152:153], 0x200
	v_mov_b64_e32 v[154:155], 0x1ff
	s_add_i32 s64, 0, 0x10000
	s_add_i32 s65, 0, 0x14000
	v_add_u32_e32 v166, 0, v4
	s_lshl_b32 s16, s8, 1
	v_lshlrev_b32_e32 v144, 1, v0
	s_mov_b32 s66, 0
	s_barrier
	s_branch .LBB0_885

.LBB0_896:
	v_add_u32_e32 v167, s64, v165
	ds_read_b128 v[132:135], v167
	ds_read_b128 v[156:159], v167 offset:1024
	ds_read_b128 v[160:163], v167 offset:2048
	ds_read_b128 v[168:171], v167 offset:3072
	v_add_u32_e32 v167, s65, v165
	ds_read_b128 v[172:175], v167
	ds_read_b128 v[176:179], v167 offset:1024
	ds_read_b128 v[180:183], v167 offset:2048
	ds_read_b128 v[184:187], v167 offset:3072
	s_add_u32 s8, s46, 0x100
	s_addc_u32 s81, s47, 0
	s_and_b64 s[46:47], exec, s[44:45]
	s_cselect_b32 s47, s5, s81
	s_cselect_b32 s46, s4, s8
	s_add_u32 s8, s80, 0x100
	s_addc_u32 s79, s79, 0
	s_and_b64 s[44:45], exec, s[44:45]
	s_cselect_b32 s45, s21, s79
	s_cselect_b32 s44, s20, s8
	v_lshl_add_u64 v[220:221], v[128:129], 0, s[36:37]
	s_add_i32 m0, s51, 0xc000
	ds_read_b128 v[188:191], v166
	ds_read_b128 v[192:195], v166 offset:1024
	ds_read_b128 v[196:199], v166 offset:2048
	ds_read_b128 v[200:203], v166 offset:3072
	ds_read_b128 v[204:207], v166 offset:4096
	ds_read_b128 v[208:211], v166 offset:5120
	ds_read_b128 v[212:215], v166 offset:6144
	ds_read_b128 v[216:219], v166 offset:7168
	global_load_lds_dwordx4 v[220:221], off
	v_lshl_add_u64 v[220:221], v[130:131], 0, s[36:37]
	s_add_i32 m0, s51, 0xe000
	s_nop 0
	global_load_lds_dwordx4 v[220:221], off
	s_waitcnt vmcnt(8)
	s_waitcnt lgkmcnt(0)
	s_barrier
	s_setprio 1
	s_waitcnt lgkmcnt(0)
	v_mfma_f32_16x16x32_bf16 v[124:127], v[132:135], v[188:191], v[124:127]
	v_mfma_f32_16x16x32_bf16 v[120:123], v[160:163], v[188:191], v[120:123]
	v_mfma_f32_16x16x32_bf16 v[108:111], v[132:135], v[196:199], v[108:111]
	v_mfma_f32_16x16x32_bf16 v[104:107], v[160:163], v[196:199], v[104:107]
	v_mfma_f32_16x16x32_bf16 v[92:95], v[132:135], v[204:207], v[92:95]
	v_mfma_f32_16x16x32_bf16 v[88:91], v[160:163], v[204:207], v[88:91]
	v_mfma_f32_16x16x32_bf16 v[76:79], v[132:135], v[212:215], v[76:79]
	v_mfma_f32_16x16x32_bf16 v[72:75], v[160:163], v[212:215], v[72:75]
	v_mfma_f32_16x16x32_bf16 v[124:127], v[156:159], v[192:195], v[124:127]
	v_mfma_f32_16x16x32_bf16 v[120:123], v[168:171], v[192:195], v[120:123]
	v_mfma_f32_16x16x32_bf16 v[108:111], v[156:159], v[200:203], v[108:111]
	v_mfma_f32_16x16x32_bf16 v[104:107], v[168:171], v[200:203], v[104:107]
	v_mfma_f32_16x16x32_bf16 v[92:95], v[156:159], v[208:211], v[92:95]
	v_mfma_f32_16x16x32_bf16 v[88:91], v[168:171], v[208:211], v[88:91]
	v_mfma_f32_16x16x32_bf16 v[76:79], v[156:159], v[216:219], v[76:79]
	v_mfma_f32_16x16x32_bf16 v[72:75], v[168:171], v[216:219], v[72:75]
	s_setprio 0
	s_setprio 1
	v_mfma_f32_16x16x32_bf16 v[116:119], v[172:175], v[188:191], v[116:119]
	v_mfma_f32_16x16x32_bf16 v[112:115], v[180:183], v[188:191], v[112:115]
	v_mfma_f32_16x16x32_bf16 v[100:103], v[172:175], v[196:199], v[100:103]
	v_mfma_f32_16x16x32_bf16 v[96:99], v[180:183], v[196:199], v[96:99]
	v_mfma_f32_16x16x32_bf16 v[84:87], v[172:175], v[204:207], v[84:87]
	v_mfma_f32_16x16x32_bf16 v[80:83], v[180:183], v[204:207], v[80:83]
	v_mfma_f32_16x16x32_bf16 v[68:71], v[172:175], v[212:215], v[68:71]
	v_mfma_f32_16x16x32_bf16 v[64:67], v[180:183], v[212:215], v[64:67]
	v_mfma_f32_16x16x32_bf16 v[116:119], v[176:179], v[192:195], v[116:119]
	v_mfma_f32_16x16x32_bf16 v[112:115], v[184:187], v[192:195], v[112:115]
	v_mfma_f32_16x16x32_bf16 v[100:103], v[176:179], v[200:203], v[100:103]
	v_mfma_f32_16x16x32_bf16 v[96:99], v[184:187], v[200:203], v[96:99]
	v_mfma_f32_16x16x32_bf16 v[84:87], v[176:179], v[208:211], v[84:87]
	v_mfma_f32_16x16x32_bf16 v[80:83], v[184:187], v[208:211], v[80:83]
	v_mfma_f32_16x16x32_bf16 v[68:71], v[176:179], v[216:219], v[68:71]
	v_mfma_f32_16x16x32_bf16 v[64:67], v[184:187], v[216:219], v[64:67]
	s_setprio 0
	s_barrier
	s_add_i32 s8, s64, s50
	s_mov_b32 m0, s8
	ds_read_b128 v[188:191], v166 offset:16384
	ds_read_b128 v[192:195], v166 offset:17408
	ds_read_b128 v[196:199], v166 offset:18432
	ds_read_b128 v[200:203], v166 offset:19456
	ds_read_b128 v[204:207], v166 offset:20480
	ds_read_b128 v[208:211], v166 offset:21504
	ds_read_b128 v[212:215], v166 offset:22528
	ds_read_b128 v[216:219], v166 offset:23552
	global_load_lds_dwordx4 v138, s[44:45]
	s_add_i32 m0, s8, 0x2000
	s_nop 0
	global_load_lds_dwordx4 v142, s[44:45]
	s_add_u32 s44, s44, 0xb0000
	s_addc_u32 s45, s45, 0
	s_add_i32 s8, s65, s50
	s_mov_b32 m0, s8
	s_nop 0
	global_load_lds_dwordx4 v138, s[44:45]
	s_add_i32 m0, s8, 0x2000
	s_nop 0
	global_load_lds_dwordx4 v142, s[44:45]
	s_mov_b32 m0, s51
	s_nop 0
	global_load_lds_dwordx4 v136, s[46:47]
	s_mov_b32 m0, s52
	s_nop 0
	global_load_lds_dwordx4 v140, s[46:47]
	s_waitcnt vmcnt(8)
	s_waitcnt lgkmcnt(0)
	s_barrier
	s_setprio 1
	s_waitcnt lgkmcnt(0)
	v_mfma_f32_16x16x32_bf16 v[60:63], v[132:135], v[188:191], v[60:63]
	v_mfma_f32_16x16x32_bf16 v[56:59], v[160:163], v[188:191], v[56:59]
	v_mfma_f32_16x16x32_bf16 v[44:47], v[132:135], v[196:199], v[44:47]
	v_mfma_f32_16x16x32_bf16 v[40:43], v[160:163], v[196:199], v[40:43]
	v_mfma_f32_16x16x32_bf16 v[28:31], v[132:135], v[204:207], v[28:31]
	v_mfma_f32_16x16x32_bf16 v[24:27], v[160:163], v[204:207], v[24:27]
	v_mfma_f32_16x16x32_bf16 v[12:15], v[132:135], v[212:215], v[12:15]
	v_mfma_f32_16x16x32_bf16 v[8:11], v[160:163], v[212:215], v[8:11]
	v_mfma_f32_16x16x32_bf16 v[60:63], v[156:159], v[192:195], v[60:63]
	v_mfma_f32_16x16x32_bf16 v[56:59], v[168:171], v[192:195], v[56:59]
	v_mfma_f32_16x16x32_bf16 v[44:47], v[156:159], v[200:203], v[44:47]
	v_mfma_f32_16x16x32_bf16 v[40:43], v[168:171], v[200:203], v[40:43]
	v_mfma_f32_16x16x32_bf16 v[28:31], v[156:159], v[208:211], v[28:31]
	v_mfma_f32_16x16x32_bf16 v[24:27], v[168:171], v[208:211], v[24:27]
	v_mfma_f32_16x16x32_bf16 v[12:15], v[156:159], v[216:219], v[12:15]
	v_mfma_f32_16x16x32_bf16 v[8:11], v[168:171], v[216:219], v[8:11]
	s_setprio 0
	s_setprio 1
	v_mfma_f32_16x16x32_bf16 v[52:55], v[172:175], v[188:191], v[52:55]
	v_mfma_f32_16x16x32_bf16 v[48:51], v[180:183], v[188:191], v[48:51]
	v_mfma_f32_16x16x32_bf16 v[36:39], v[172:175], v[196:199], v[36:39]
	v_mfma_f32_16x16x32_bf16 v[32:35], v[180:183], v[196:199], v[32:35]
	v_mfma_f32_16x16x32_bf16 v[20:23], v[172:175], v[204:207], v[20:23]
	v_mfma_f32_16x16x32_bf16 v[16:19], v[180:183], v[204:207], v[16:19]
	v_mfma_f32_16x16x32_bf16 v[4:7], v[172:175], v[212:215], v[4:7]
	v_mfma_f32_16x16x32_bf16 v[0:3], v[180:183], v[212:215], v[0:3]
	v_mfma_f32_16x16x32_bf16 v[52:55], v[176:179], v[192:195], v[52:55]
	v_mfma_f32_16x16x32_bf16 v[48:51], v[184:187], v[192:195], v[48:51]
	v_mfma_f32_16x16x32_bf16 v[36:39], v[176:179], v[200:203], v[36:39]
	v_mfma_f32_16x16x32_bf16 v[32:35], v[184:187], v[200:203], v[32:35]
	v_mfma_f32_16x16x32_bf16 v[20:23], v[176:179], v[208:211], v[20:23]
	v_mfma_f32_16x16x32_bf16 v[16:19], v[184:187], v[208:211], v[16:19]
	v_mfma_f32_16x16x32_bf16 v[4:7], v[176:179], v[216:219], v[4:7]
	v_mfma_f32_16x16x32_bf16 v[0:3], v[184:187], v[216:219], v[0:3]
	s_setprio 0
	s_barrier
	s_add_i32 s8, 0, 0x18000
	v_add_u32_e32 v167, s8, v165
	s_add_i32 s79, 0, 0x1c000
	ds_read_b128 v[132:135], v167
	ds_read_b128 v[156:159], v167 offset:1024
	ds_read_b128 v[160:163], v167 offset:2048
	ds_read_b128 v[168:171], v167 offset:3072
	v_add_u32_e32 v167, s79, v165
	ds_read_b128 v[172:175], v167
	ds_read_b128 v[176:179], v167 offset:1024
	ds_read_b128 v[180:183], v167 offset:2048
	ds_read_b128 v[184:187], v167 offset:3072
	s_add_u32 s44, s46, 0xb0000
	s_addc_u32 s45, s47, 0
	s_mov_b32 m0, s53
	ds_read_b128 v[188:191], v166 offset:32768
	ds_read_b128 v[192:195], v166 offset:33792
	ds_read_b128 v[196:199], v166 offset:34816
	ds_read_b128 v[200:203], v166 offset:35840
	ds_read_b128 v[204:207], v166 offset:36864
	ds_read_b128 v[208:211], v166 offset:37888
	ds_read_b128 v[212:215], v166 offset:38912
	ds_read_b128 v[216:219], v166 offset:39936
	global_load_lds_dwordx4 v136, s[44:45]
	s_mov_b32 m0, s54
	s_nop 0
	global_load_lds_dwordx4 v140, s[44:45]
	s_waitcnt vmcnt(8)
	s_waitcnt lgkmcnt(0)
	s_barrier
	s_setprio 1
	s_waitcnt lgkmcnt(0)
	v_mfma_f32_16x16x32_bf16 v[124:127], v[132:135], v[188:191], v[124:127]
	v_mfma_f32_16x16x32_bf16 v[120:123], v[160:163], v[188:191], v[120:123]
	v_mfma_f32_16x16x32_bf16 v[108:111], v[132:135], v[196:199], v[108:111]
	v_mfma_f32_16x16x32_bf16 v[104:107], v[160:163], v[196:199], v[104:107]
	v_mfma_f32_16x16x32_bf16 v[92:95], v[132:135], v[204:207], v[92:95]
	v_mfma_f32_16x16x32_bf16 v[88:91], v[160:163], v[204:207], v[88:91]
	v_mfma_f32_16x16x32_bf16 v[76:79], v[132:135], v[212:215], v[76:79]
	v_mfma_f32_16x16x32_bf16 v[72:75], v[160:163], v[212:215], v[72:75]
	v_mfma_f32_16x16x32_bf16 v[124:127], v[156:159], v[192:195], v[124:127]
	v_mfma_f32_16x16x32_bf16 v[120:123], v[168:171], v[192:195], v[120:123]
	v_mfma_f32_16x16x32_bf16 v[108:111], v[156:159], v[200:203], v[108:111]
	v_mfma_f32_16x16x32_bf16 v[104:107], v[168:171], v[200:203], v[104:107]
	v_mfma_f32_16x16x32_bf16 v[92:95], v[156:159], v[208:211], v[92:95]
	v_mfma_f32_16x16x32_bf16 v[88:91], v[168:171], v[208:211], v[88:91]
	v_mfma_f32_16x16x32_bf16 v[76:79], v[156:159], v[216:219], v[76:79]
	v_mfma_f32_16x16x32_bf16 v[72:75], v[168:171], v[216:219], v[72:75]
	s_setprio 0
	s_setprio 1
	v_mfma_f32_16x16x32_bf16 v[116:119], v[172:175], v[188:191], v[116:119]
	v_mfma_f32_16x16x32_bf16 v[112:115], v[180:183], v[188:191], v[112:115]
	v_mfma_f32_16x16x32_bf16 v[100:103], v[172:175], v[196:199], v[100:103]
	v_mfma_f32_16x16x32_bf16 v[96:99], v[180:183], v[196:199], v[96:99]
	v_mfma_f32_16x16x32_bf16 v[84:87], v[172:175], v[204:207], v[84:87]
	v_mfma_f32_16x16x32_bf16 v[80:83], v[180:183], v[204:207], v[80:83]
	v_mfma_f32_16x16x32_bf16 v[68:71], v[172:175], v[212:215], v[68:71]
	v_mfma_f32_16x16x32_bf16 v[64:67], v[180:183], v[212:215], v[64:67]
	v_mfma_f32_16x16x32_bf16 v[116:119], v[176:179], v[192:195], v[116:119]
	v_mfma_f32_16x16x32_bf16 v[112:115], v[184:187], v[192:195], v[112:115]
	v_mfma_f32_16x16x32_bf16 v[100:103], v[176:179], v[200:203], v[100:103]
	v_mfma_f32_16x16x32_bf16 v[96:99], v[184:187], v[200:203], v[96:99]
	v_mfma_f32_16x16x32_bf16 v[84:87], v[176:179], v[208:211], v[84:87]
	v_mfma_f32_16x16x32_bf16 v[80:83], v[184:187], v[208:211], v[80:83]
	v_mfma_f32_16x16x32_bf16 v[68:71], v[176:179], v[216:219], v[68:71]
	v_mfma_f32_16x16x32_bf16 v[64:67], v[184:187], v[216:219], v[64:67]
	s_setprio 0
	s_barrier
	s_add_i32 s8, s8, s50
	s_mov_b32 m0, s8
	ds_read_b128 v[188:191], v166 offset:49152
	ds_read_b128 v[192:195], v166 offset:50176
	ds_read_b128 v[196:199], v166 offset:51200
	ds_read_b128 v[200:203], v166 offset:52224
	ds_read_b128 v[204:207], v166 offset:53248
	ds_read_b128 v[208:211], v166 offset:54272
	ds_read_b128 v[212:215], v166 offset:55296
	ds_read_b128 v[216:219], v166 offset:56320
	global_load_lds_dwordx4 v138, s[40:41]
	s_add_i32 m0, s8, 0x2000
	s_nop 0
	global_load_lds_dwordx4 v142, s[40:41]
	s_add_u32 s40, s40, 0xb0000
	s_addc_u32 s41, s41, 0
	s_add_i32 s8, s79, s50
	s_mov_b32 m0, s8
	s_nop 0
	global_load_lds_dwordx4 v138, s[40:41]
	s_add_i32 m0, s8, 0x2000
	s_nop 0
	global_load_lds_dwordx4 v142, s[40:41]
	s_mov_b32 m0, s60
	s_nop 0
	global_load_lds_dwordx4 v136, s[38:39]
	s_mov_b32 m0, s61
	s_nop 0
	global_load_lds_dwordx4 v140, s[38:39]
	s_waitcnt vmcnt(8)
	s_waitcnt lgkmcnt(0)
	s_barrier
	s_setprio 1
	s_waitcnt lgkmcnt(0)
	v_mfma_f32_16x16x32_bf16 v[60:63], v[132:135], v[188:191], v[60:63]
	v_mfma_f32_16x16x32_bf16 v[56:59], v[160:163], v[188:191], v[56:59]
	v_mfma_f32_16x16x32_bf16 v[44:47], v[132:135], v[196:199], v[44:47]
	v_mfma_f32_16x16x32_bf16 v[40:43], v[160:163], v[196:199], v[40:43]
	v_mfma_f32_16x16x32_bf16 v[28:31], v[132:135], v[204:207], v[28:31]
	v_mfma_f32_16x16x32_bf16 v[24:27], v[160:163], v[204:207], v[24:27]
	v_mfma_f32_16x16x32_bf16 v[12:15], v[132:135], v[212:215], v[12:15]
	v_mfma_f32_16x16x32_bf16 v[8:11], v[160:163], v[212:215], v[8:11]
	v_mfma_f32_16x16x32_bf16 v[60:63], v[156:159], v[192:195], v[60:63]
	v_mfma_f32_16x16x32_bf16 v[56:59], v[168:171], v[192:195], v[56:59]
	v_mfma_f32_16x16x32_bf16 v[44:47], v[156:159], v[200:203], v[44:47]
	v_mfma_f32_16x16x32_bf16 v[40:43], v[168:171], v[200:203], v[40:43]
	v_mfma_f32_16x16x32_bf16 v[28:31], v[156:159], v[208:211], v[28:31]
	v_mfma_f32_16x16x32_bf16 v[24:27], v[168:171], v[208:211], v[24:27]
	v_mfma_f32_16x16x32_bf16 v[12:15], v[156:159], v[216:219], v[12:15]
	v_mfma_f32_16x16x32_bf16 v[8:11], v[168:171], v[216:219], v[8:11]
	s_setprio 0
	s_setprio 1
	v_mfma_f32_16x16x32_bf16 v[52:55], v[172:175], v[188:191], v[52:55]
	v_mfma_f32_16x16x32_bf16 v[48:51], v[180:183], v[188:191], v[48:51]
	v_mfma_f32_16x16x32_bf16 v[36:39], v[172:175], v[196:199], v[36:39]
	v_mfma_f32_16x16x32_bf16 v[32:35], v[180:183], v[196:199], v[32:35]
	v_mfma_f32_16x16x32_bf16 v[20:23], v[172:175], v[204:207], v[20:23]
	v_mfma_f32_16x16x32_bf16 v[16:19], v[180:183], v[204:207], v[16:19]
	v_mfma_f32_16x16x32_bf16 v[4:7], v[172:175], v[212:215], v[4:7]
	v_mfma_f32_16x16x32_bf16 v[0:3], v[180:183], v[212:215], v[0:3]
	v_mfma_f32_16x16x32_bf16 v[52:55], v[176:179], v[192:195], v[52:55]
	v_mfma_f32_16x16x32_bf16 v[48:51], v[184:187], v[192:195], v[48:51]
	v_mfma_f32_16x16x32_bf16 v[36:39], v[176:179], v[200:203], v[36:39]
	v_mfma_f32_16x16x32_bf16 v[32:35], v[184:187], v[200:203], v[32:35]
	v_mfma_f32_16x16x32_bf16 v[20:23], v[176:179], v[208:211], v[20:23]
	v_mfma_f32_16x16x32_bf16 v[16:19], v[184:187], v[208:211], v[16:19]
	v_mfma_f32_16x16x32_bf16 v[4:7], v[176:179], v[216:219], v[4:7]
	v_mfma_f32_16x16x32_bf16 v[0:3], v[184:187], v[216:219], v[0:3]
	s_setprio 0
	s_barrier
	s_add_i32 s8, s78, 2
	s_add_u32 s36, s36, 0x100
	s_addc_u32 s37, s37, 0
	s_cmp_gt_u32 s78, 41
	s_mov_b32 s78, s8
	s_cbranch_scc1 .LBB0_903

.LBB0_986:
	s_lshl_b32 s1, s1, 5
	s_mov_b64 s[12:13], 0x80
	s_and_b32 s1, s1, 0x60
	s_add_i32 m0, s49, 0x18000
	v_lshl_add_u64 v[6:7], v[6:7], 0, s[12:13]
	s_lshl_b32 s18, s15, 13
	s_lshl_b32 s19, s1, 7
	s_waitcnt vmcnt(2)
	s_barrier
	global_load_lds_dwordx4 v[6:7], off
	v_lshl_add_u64 v[4:5], v[4:5], 0, s[12:13]
	s_add_i32 m0, s49, 0x1a000
	s_add_i32 s53, s49, 0x8000
	s_add_i32 s54, s49, 0xa000
	global_load_lds_dwordx4 v[4:5], off
	v_lshl_add_u64 v[0:1], v[0:1], 0, s[12:13]
	s_mov_b32 m0, s53
	s_add_u32 s16, s38, 0x10080
	global_load_lds_dwordx4 v[0:1], off
	v_lshl_add_u64 v[0:1], v[2:3], 0, s[12:13]
	s_mov_b32 m0, s54
	s_addc_u32 s17, s39, 0
	global_load_lds_dwordx4 v[0:1], off
	s_add_i32 m0, s49, 0x1c000
	s_nop 0
	global_load_lds_dwordx4 v130, s[16:17]
	s_add_i32 m0, s49, 0x1e000
	s_cmpk_lt_u32 s14, 0x100
	global_load_lds_dwordx4 v134, s[16:17]
	v_lshrrev_b32_e32 v0, 1, v8
	v_and_b32_e32 v0, 24, v0
	v_and_b32_e32 v1, 15, v8
	v_lshlrev_b32_e32 v2, 1, v0
	v_lshl_or_b32 v143, s15, 6, v1
	v_lshl_or_b32 v1, v1, 6, v2
	v_lshlrev_b32_e32 v2, 2, v8
	s_cselect_b64 s[14:15], -1, 0
	s_ashr_i32 s55, s3, 31
	v_and_b32_e32 v2, 32, v2
	s_add_u32 s16, s2, s3
	v_bitop3_b32 v144, v1, s19, v2 bitop3:0xde
	s_waitcnt vmcnt(6)
	s_addc_u32 s17, s8, s55
	s_add_i32 s58, 0, 0x10000
	s_add_i32 s60, 0, 0x14000
	v_bitop3_b32 v3, v1, s18, v2 bitop3:0xde
	v_add_u32_e32 v145, s58, v144
	v_add_u32_e32 v146, s60, v144
	s_add_i32 s58, s58, s48
	s_add_i32 s60, s60, s48
	s_add_i32 s62, 0, 0x18000
	s_sext_i32_i8 s27, s0
	v_add_u32_e32 v147, 0, v3
	s_mov_b64 s[18:19], 0x100
	s_mov_b64 s[20:21], 0x180
	s_lshl_b32 s8, s1, 1
	v_lshlrev_b32_e32 v136, 1, v0
	s_add_i32 s56, s49, 0xc000
	s_add_i32 s57, s49, 0xe000
	s_add_i32 s59, s58, 0x2000
	s_add_i32 s61, s60, 0x2000
	v_add_u32_e32 v148, s62, v144
	s_barrier
	s_branch .LBB0_989

.LBB0_995:
	ds_read_b128 v[0:3], v145
	ds_read_b128 v[4:7], v145 offset:1024
	ds_read_b128 v[8:11], v145 offset:2048
	ds_read_b128 v[12:15], v145 offset:3072
	ds_read_b128 v[16:19], v146
	ds_read_b128 v[20:23], v146 offset:1024
	ds_read_b128 v[24:27], v146 offset:2048
	ds_read_b128 v[28:31], v146 offset:3072
	s_ashr_i32 s25, s24, 31
	s_lshl_b64 s[28:29], s[24:25], 17
	s_add_u32 s28, s44, s28
	s_addc_u32 s29, s45, s29
	s_and_b64 s[30:31], s[0:1], exec
	s_cselect_b32 s43, s29, s37
	s_cselect_b32 s42, s28, s36
	s_ashr_i32 s23, s22, 31
	s_lshl_b64 s[30:31], s[22:23], 17
	s_add_u32 s30, s46, s30
	s_addc_u32 s31, s47, s31
	s_and_b64 s[40:41], s[0:1], exec
	s_cselect_b32 s41, s31, s39
	s_cselect_b32 s40, s30, s38
	s_add_u32 s64, s36, 0x10080
	s_addc_u32 s65, s37, 0
	s_mov_b32 m0, s56
	ds_read_b128 v[32:35], v147
	ds_read_b128 v[36:39], v147 offset:1024
	ds_read_b128 v[40:43], v147 offset:2048
	ds_read_b128 v[44:47], v147 offset:3072
	ds_read_b128 v[48:51], v147 offset:4096
	ds_read_b128 v[52:55], v147 offset:5120
	ds_read_b128 v[56:59], v147 offset:6144
	ds_read_b128 v[60:63], v147 offset:7168
	global_load_lds_dwordx4 v128, s[64:65]
	s_mov_b32 m0, s57
	s_nop 0
	global_load_lds_dwordx4 v132, s[64:65]
	s_waitcnt vmcnt(8)
	s_waitcnt lgkmcnt(0)
	s_barrier
	s_setprio 1
	s_waitcnt lgkmcnt(0)
	v_mfma_f32_16x16x32_bf16 v[64:67], v[0:3], v[32:35], 0
	v_mfma_f32_16x16x32_bf16 v[68:71], v[8:11], v[32:35], 0
	v_mfma_f32_16x16x32_bf16 v[72:75], v[0:3], v[40:43], 0
	v_mfma_f32_16x16x32_bf16 v[76:79], v[8:11], v[40:43], 0
	v_mfma_f32_16x16x32_bf16 v[80:83], v[0:3], v[48:51], 0
	v_mfma_f32_16x16x32_bf16 v[84:87], v[8:11], v[48:51], 0
	v_mfma_f32_16x16x32_bf16 v[88:91], v[0:3], v[56:59], 0
	v_mfma_f32_16x16x32_bf16 v[92:95], v[8:11], v[56:59], 0
	v_mfma_f32_16x16x32_bf16 v[64:67], v[4:7], v[36:39], v[64:67]
	v_mfma_f32_16x16x32_bf16 v[68:71], v[12:15], v[36:39], v[68:71]
	v_mfma_f32_16x16x32_bf16 v[72:75], v[4:7], v[44:47], v[72:75]
	v_mfma_f32_16x16x32_bf16 v[76:79], v[12:15], v[44:47], v[76:79]
	v_mfma_f32_16x16x32_bf16 v[80:83], v[4:7], v[52:55], v[80:83]
	v_mfma_f32_16x16x32_bf16 v[84:87], v[12:15], v[52:55], v[84:87]
	v_mfma_f32_16x16x32_bf16 v[88:91], v[4:7], v[60:63], v[88:91]
	v_mfma_f32_16x16x32_bf16 v[92:95], v[12:15], v[60:63], v[92:95]
	s_setprio 0
	s_setprio 1
	v_mfma_f32_16x16x32_bf16 v[96:99], v[16:19], v[32:35], 0
	v_mfma_f32_16x16x32_bf16 v[32:35], v[24:27], v[32:35], 0
	v_mfma_f32_16x16x32_bf16 v[96:99], v[20:23], v[36:39], v[96:99]
	v_mfma_f32_16x16x32_bf16 v[32:35], v[28:31], v[36:39], v[32:35]
	v_mfma_f32_16x16x32_bf16 v[36:39], v[16:19], v[40:43], 0
	v_mfma_f32_16x16x32_bf16 v[40:43], v[24:27], v[40:43], 0
	v_mfma_f32_16x16x32_bf16 v[36:39], v[20:23], v[44:47], v[36:39]
	v_mfma_f32_16x16x32_bf16 v[40:43], v[28:31], v[44:47], v[40:43]
	v_mfma_f32_16x16x32_bf16 v[44:47], v[16:19], v[48:51], 0
	v_mfma_f32_16x16x32_bf16 v[48:51], v[24:27], v[48:51], 0
	v_mfma_f32_16x16x32_bf16 v[44:47], v[20:23], v[52:55], v[44:47]
	v_mfma_f32_16x16x32_bf16 v[48:51], v[28:31], v[52:55], v[48:51]
	v_mfma_f32_16x16x32_bf16 v[52:55], v[16:19], v[56:59], 0
	v_mfma_f32_16x16x32_bf16 v[56:59], v[24:27], v[56:59], 0
	v_mfma_f32_16x16x32_bf16 v[52:55], v[20:23], v[60:63], v[52:55]
	v_mfma_f32_16x16x32_bf16 v[56:59], v[28:31], v[60:63], v[56:59]
	s_setprio 0
	s_barrier
	v_lshl_add_u64 v[214:215], s[38:39], 0, v[130:131]
	s_mov_b32 m0, s58
	v_lshl_add_u64 v[150:151], v[214:215], 0, s[18:19]
	v_lshl_add_u64 v[216:217], s[38:39], 0, v[134:135]
	s_add_u32 s64, s38, 0x10100
	ds_read_b128 v[60:63], v147 offset:16384
	ds_read_b128 v[100:103], v147 offset:17408
	ds_read_b128 v[104:107], v147 offset:18432
	ds_read_b128 v[108:111], v147 offset:19456
	ds_read_b128 v[112:115], v147 offset:20480
	ds_read_b128 v[116:119], v147 offset:21504
	ds_read_b128 v[120:123], v147 offset:22528
	ds_read_b128 v[124:127], v147 offset:23552
	global_load_lds_dwordx4 v[150:151], off
	v_lshl_add_u64 v[150:151], v[216:217], 0, s[18:19]
	s_mov_b32 m0, s59
	s_addc_u32 s65, s39, 0
	global_load_lds_dwordx4 v[150:151], off
	s_mov_b32 m0, s60
	v_lshl_add_u64 v[218:219], s[36:37], 0, v[128:129]
	global_load_lds_dwordx4 v130, s[64:65]
	s_mov_b32 m0, s61
	v_lshl_add_u64 v[220:221], s[36:37], 0, v[132:133]
	global_load_lds_dwordx4 v134, s[64:65]
	v_lshl_add_u64 v[150:151], v[218:219], 0, s[18:19]
	s_mov_b32 m0, s49
	s_nop 0
	global_load_lds_dwordx4 v[150:151], off
	v_lshl_add_u64 v[150:151], v[220:221], 0, s[18:19]
	s_mov_b32 m0, s50
	s_nop 0
	global_load_lds_dwordx4 v[150:151], off
	s_waitcnt vmcnt(8)
	s_waitcnt lgkmcnt(0)
	s_barrier
	s_setprio 1
	s_waitcnt lgkmcnt(0)
	v_mfma_f32_16x16x32_bf16 v[150:153], v[0:3], v[60:63], 0
	v_mfma_f32_16x16x32_bf16 v[158:161], v[0:3], v[104:107], 0
	v_mfma_f32_16x16x32_bf16 v[166:169], v[0:3], v[112:115], 0
	v_mfma_f32_16x16x32_bf16 v[0:3], v[0:3], v[120:123], 0
	v_mfma_f32_16x16x32_bf16 v[150:153], v[4:7], v[100:103], v[150:153]
	v_mfma_f32_16x16x32_bf16 v[158:161], v[4:7], v[108:111], v[158:161]
	v_mfma_f32_16x16x32_bf16 v[166:169], v[4:7], v[116:119], v[166:169]
	v_mfma_f32_16x16x32_bf16 v[0:3], v[4:7], v[124:127], v[0:3]
	v_mfma_f32_16x16x32_bf16 v[4:7], v[8:11], v[120:123], 0
	v_mfma_f32_16x16x32_bf16 v[154:157], v[8:11], v[60:63], 0
	v_mfma_f32_16x16x32_bf16 v[162:165], v[8:11], v[104:107], 0
	v_mfma_f32_16x16x32_bf16 v[170:173], v[8:11], v[112:115], 0
	v_mfma_f32_16x16x32_bf16 v[4:7], v[12:15], v[124:127], v[4:7]
	v_mfma_f32_16x16x32_bf16 v[154:157], v[12:15], v[100:103], v[154:157]
	v_mfma_f32_16x16x32_bf16 v[162:165], v[12:15], v[108:111], v[162:165]
	v_mfma_f32_16x16x32_bf16 v[170:173], v[12:15], v[116:119], v[170:173]
	s_setprio 0
	s_setprio 1
	v_mfma_f32_16x16x32_bf16 v[8:11], v[16:19], v[60:63], 0
	v_mfma_f32_16x16x32_bf16 v[12:15], v[24:27], v[60:63], 0
	v_mfma_f32_16x16x32_bf16 v[8:11], v[20:23], v[100:103], v[8:11]
	v_mfma_f32_16x16x32_bf16 v[12:15], v[28:31], v[100:103], v[12:15]
	v_mfma_f32_16x16x32_bf16 v[60:63], v[16:19], v[104:107], 0
	v_mfma_f32_16x16x32_bf16 v[100:103], v[24:27], v[104:107], 0
	v_mfma_f32_16x16x32_bf16 v[104:107], v[16:19], v[112:115], 0
	v_mfma_f32_16x16x32_bf16 v[16:19], v[16:19], v[120:123], 0
	v_mfma_f32_16x16x32_bf16 v[60:63], v[20:23], v[108:111], v[60:63]
	v_mfma_f32_16x16x32_bf16 v[100:103], v[28:31], v[108:111], v[100:103]
	v_mfma_f32_16x16x32_bf16 v[104:107], v[20:23], v[116:119], v[104:107]
	v_mfma_f32_16x16x32_bf16 v[108:111], v[24:27], v[112:115], 0
	v_mfma_f32_16x16x32_bf16 v[16:19], v[20:23], v[124:127], v[16:19]
	v_mfma_f32_16x16x32_bf16 v[20:23], v[24:27], v[120:123], 0
	v_mfma_f32_16x16x32_bf16 v[108:111], v[28:31], v[116:119], v[108:111]
	v_mfma_f32_16x16x32_bf16 v[20:23], v[28:31], v[124:127], v[20:23]
	s_setprio 0
	s_barrier
	s_add_i32 s25, 0, 0x1c000
	v_add_u32_e32 v149, s25, v144
	ds_read_b128 v[24:27], v148
	ds_read_b128 v[28:31], v148 offset:1024
	ds_read_b128 v[112:115], v148 offset:2048
	ds_read_b128 v[116:119], v148 offset:3072
	ds_read_b128 v[120:123], v149
	ds_read_b128 v[124:127], v149 offset:1024
	ds_read_b128 v[174:177], v149 offset:2048
	ds_read_b128 v[178:181], v149 offset:3072
	s_add_u32 s64, s36, 0x10100
	s_addc_u32 s65, s37, 0
	s_mov_b32 m0, s51
	ds_read_b128 v[182:185], v147 offset:32768
	ds_read_b128 v[186:189], v147 offset:33792
	ds_read_b128 v[190:193], v147 offset:34816
	ds_read_b128 v[194:197], v147 offset:35840
	ds_read_b128 v[198:201], v147 offset:36864
	ds_read_b128 v[202:205], v147 offset:37888
	ds_read_b128 v[206:209], v147 offset:38912
	ds_read_b128 v[210:213], v147 offset:39936
	global_load_lds_dwordx4 v128, s[64:65]
	s_mov_b32 m0, s52
	s_nop 0
	global_load_lds_dwordx4 v132, s[64:65]
	s_waitcnt vmcnt(8)
	s_waitcnt lgkmcnt(0)
	s_barrier
	s_setprio 1
	s_waitcnt lgkmcnt(0)
	v_mfma_f32_16x16x32_bf16 v[64:67], v[24:27], v[182:185], v[64:67]
	v_mfma_f32_16x16x32_bf16 v[68:71], v[112:115], v[182:185], v[68:71]
	v_mfma_f32_16x16x32_bf16 v[72:75], v[24:27], v[190:193], v[72:75]
	v_mfma_f32_16x16x32_bf16 v[76:79], v[112:115], v[190:193], v[76:79]
	v_mfma_f32_16x16x32_bf16 v[80:83], v[24:27], v[198:201], v[80:83]
	v_mfma_f32_16x16x32_bf16 v[84:87], v[112:115], v[198:201], v[84:87]
	v_mfma_f32_16x16x32_bf16 v[88:91], v[24:27], v[206:209], v[88:91]
	v_mfma_f32_16x16x32_bf16 v[92:95], v[112:115], v[206:209], v[92:95]
	v_mfma_f32_16x16x32_bf16 v[64:67], v[28:31], v[186:189], v[64:67]
	v_mfma_f32_16x16x32_bf16 v[68:71], v[116:119], v[186:189], v[68:71]
	v_mfma_f32_16x16x32_bf16 v[72:75], v[28:31], v[194:197], v[72:75]
	v_mfma_f32_16x16x32_bf16 v[76:79], v[116:119], v[194:197], v[76:79]
	v_mfma_f32_16x16x32_bf16 v[80:83], v[28:31], v[202:205], v[80:83]
	v_mfma_f32_16x16x32_bf16 v[84:87], v[116:119], v[202:205], v[84:87]
	v_mfma_f32_16x16x32_bf16 v[88:91], v[28:31], v[210:213], v[88:91]
	v_mfma_f32_16x16x32_bf16 v[92:95], v[116:119], v[210:213], v[92:95]
	s_setprio 0
	s_setprio 1
	v_mfma_f32_16x16x32_bf16 v[96:99], v[120:123], v[182:185], v[96:99]
	v_mfma_f32_16x16x32_bf16 v[32:35], v[174:177], v[182:185], v[32:35]
	v_mfma_f32_16x16x32_bf16 v[36:39], v[120:123], v[190:193], v[36:39]
	v_mfma_f32_16x16x32_bf16 v[40:43], v[174:177], v[190:193], v[40:43]
	v_mfma_f32_16x16x32_bf16 v[44:47], v[120:123], v[198:201], v[44:47]
	v_mfma_f32_16x16x32_bf16 v[48:51], v[174:177], v[198:201], v[48:51]
	v_mfma_f32_16x16x32_bf16 v[52:55], v[120:123], v[206:209], v[52:55]
	v_mfma_f32_16x16x32_bf16 v[56:59], v[174:177], v[206:209], v[56:59]
	v_mfma_f32_16x16x32_bf16 v[96:99], v[124:127], v[186:189], v[96:99]
	v_mfma_f32_16x16x32_bf16 v[32:35], v[178:181], v[186:189], v[32:35]
	v_mfma_f32_16x16x32_bf16 v[36:39], v[124:127], v[194:197], v[36:39]
	v_mfma_f32_16x16x32_bf16 v[40:43], v[178:181], v[194:197], v[40:43]
	v_mfma_f32_16x16x32_bf16 v[44:47], v[124:127], v[202:205], v[44:47]
	v_mfma_f32_16x16x32_bf16 v[48:51], v[178:181], v[202:205], v[48:51]
	v_mfma_f32_16x16x32_bf16 v[52:55], v[124:127], v[210:213], v[52:55]
	v_mfma_f32_16x16x32_bf16 v[56:59], v[178:181], v[210:213], v[56:59]
	s_setprio 0
	s_barrier
	s_add_i32 s63, s62, s48
	s_add_i32 s23, s63, 0x2000
	v_lshl_add_u64 v[214:215], v[214:215], 0, s[20:21]
	s_mov_b32 m0, s63
	s_add_u32 s38, s38, 0x10180
	ds_read_b128 v[182:185], v147 offset:49152
	ds_read_b128 v[186:189], v147 offset:50176
	ds_read_b128 v[190:193], v147 offset:51200
	ds_read_b128 v[194:197], v147 offset:52224
	ds_read_b128 v[198:201], v147 offset:53248
	ds_read_b128 v[202:205], v147 offset:54272
	ds_read_b128 v[206:209], v147 offset:55296
	ds_read_b128 v[210:213], v147 offset:56320
	global_load_lds_dwordx4 v[214:215], off
	v_lshl_add_u64 v[214:215], v[216:217], 0, s[20:21]
	s_mov_b32 m0, s23
	s_addc_u32 s39, s39, 0
	s_add_i32 s25, s25, s48
	global_load_lds_dwordx4 v[214:215], off
	s_mov_b32 m0, s25
	s_nop 0
	global_load_lds_dwordx4 v130, s[38:39]
	v_lshl_add_u64 v[214:215], s[38:39], 0, v[134:135]
	s_add_i32 s38, s25, 0x2000
	s_mov_b32 m0, s38
	s_nop 0
	global_load_lds_dwordx4 v[214:215], off
	v_lshl_add_u64 v[214:215], v[218:219], 0, s[20:21]
	s_mov_b32 m0, s53
	s_nop 0
	global_load_lds_dwordx4 v[214:215], off
	v_lshl_add_u64 v[214:215], v[220:221], 0, s[20:21]
	s_mov_b32 m0, s54
	s_nop 0
	global_load_lds_dwordx4 v[214:215], off
	s_waitcnt vmcnt(8)
	s_waitcnt lgkmcnt(0)
	s_barrier
	s_setprio 1
	s_waitcnt lgkmcnt(0)
	v_mfma_f32_16x16x32_bf16 v[0:3], v[24:27], v[206:209], v[0:3]
	v_mfma_f32_16x16x32_bf16 v[4:7], v[112:115], v[206:209], v[4:7]
	v_mfma_f32_16x16x32_bf16 v[150:153], v[24:27], v[182:185], v[150:153]
	v_mfma_f32_16x16x32_bf16 v[154:157], v[112:115], v[182:185], v[154:157]
	v_mfma_f32_16x16x32_bf16 v[158:161], v[24:27], v[190:193], v[158:161]
	v_mfma_f32_16x16x32_bf16 v[162:165], v[112:115], v[190:193], v[162:165]
	v_mfma_f32_16x16x32_bf16 v[166:169], v[24:27], v[198:201], v[166:169]
	v_mfma_f32_16x16x32_bf16 v[170:173], v[112:115], v[198:201], v[170:173]
	v_mfma_f32_16x16x32_bf16 v[0:3], v[28:31], v[210:213], v[0:3]
	v_mfma_f32_16x16x32_bf16 v[4:7], v[116:119], v[210:213], v[4:7]
	v_mfma_f32_16x16x32_bf16 v[150:153], v[28:31], v[186:189], v[150:153]
	v_mfma_f32_16x16x32_bf16 v[154:157], v[116:119], v[186:189], v[154:157]
	v_mfma_f32_16x16x32_bf16 v[158:161], v[28:31], v[194:197], v[158:161]
	v_mfma_f32_16x16x32_bf16 v[162:165], v[116:119], v[194:197], v[162:165]
	v_mfma_f32_16x16x32_bf16 v[166:169], v[28:31], v[202:205], v[166:169]
	v_mfma_f32_16x16x32_bf16 v[170:173], v[116:119], v[202:205], v[170:173]
	s_setprio 0
	s_setprio 1
	v_mfma_f32_16x16x32_bf16 v[8:11], v[120:123], v[182:185], v[8:11]
	v_mfma_f32_16x16x32_bf16 v[12:15], v[174:177], v[182:185], v[12:15]
	v_mfma_f32_16x16x32_bf16 v[24:27], v[120:123], v[190:193], v[60:63]
	v_mfma_f32_16x16x32_bf16 v[28:31], v[174:177], v[190:193], v[100:103]
	v_mfma_f32_16x16x32_bf16 v[60:63], v[120:123], v[198:201], v[104:107]
	v_mfma_f32_16x16x32_bf16 v[100:103], v[174:177], v[198:201], v[108:111]
	v_mfma_f32_16x16x32_bf16 v[16:19], v[120:123], v[206:209], v[16:19]
	v_mfma_f32_16x16x32_bf16 v[20:23], v[174:177], v[206:209], v[20:23]
	v_mfma_f32_16x16x32_bf16 v[8:11], v[124:127], v[186:189], v[8:11]
	v_mfma_f32_16x16x32_bf16 v[12:15], v[178:181], v[186:189], v[12:15]
	v_mfma_f32_16x16x32_bf16 v[24:27], v[124:127], v[194:197], v[24:27]
	v_mfma_f32_16x16x32_bf16 v[28:31], v[178:181], v[194:197], v[28:31]
	v_mfma_f32_16x16x32_bf16 v[60:63], v[124:127], v[202:205], v[60:63]
	v_mfma_f32_16x16x32_bf16 v[100:103], v[178:181], v[202:205], v[100:103]
	v_mfma_f32_16x16x32_bf16 v[16:19], v[124:127], v[210:213], v[16:19]
	v_mfma_f32_16x16x32_bf16 v[20:23], v[178:181], v[210:213], v[20:23]
	s_setprio 0
	s_barrier
	ds_read_b128 v[104:107], v145
	ds_read_b128 v[108:111], v145 offset:1024
	ds_read_b128 v[112:115], v145 offset:2048
	ds_read_b128 v[116:119], v145 offset:3072
	ds_read_b128 v[120:123], v146
	ds_read_b128 v[124:127], v146 offset:1024
	ds_read_b128 v[174:177], v146 offset:2048
	ds_read_b128 v[178:181], v146 offset:3072
	s_add_u32 s36, s36, 0x10180
	s_addc_u32 s37, s37, 0
	s_mov_b32 m0, s56
	ds_read_b128 v[182:185], v147
	ds_read_b128 v[186:189], v147 offset:1024
	ds_read_b128 v[190:193], v147 offset:2048
	ds_read_b128 v[194:197], v147 offset:3072
	ds_read_b128 v[198:201], v147 offset:4096
	ds_read_b128 v[202:205], v147 offset:5120
	ds_read_b128 v[206:209], v147 offset:6144
	ds_read_b128 v[210:213], v147 offset:7168
	global_load_lds_dwordx4 v128, s[36:37]
	s_mov_b32 m0, s57
	s_nop 0
	global_load_lds_dwordx4 v132, s[36:37]
	s_waitcnt vmcnt(8)
	s_waitcnt lgkmcnt(0)
	s_barrier
	s_setprio 1
	s_waitcnt lgkmcnt(0)
	v_mfma_f32_16x16x32_bf16 v[64:67], v[104:107], v[182:185], v[64:67]
	v_mfma_f32_16x16x32_bf16 v[68:71], v[112:115], v[182:185], v[68:71]
	v_mfma_f32_16x16x32_bf16 v[72:75], v[104:107], v[190:193], v[72:75]
	v_mfma_f32_16x16x32_bf16 v[76:79], v[112:115], v[190:193], v[76:79]
	v_mfma_f32_16x16x32_bf16 v[80:83], v[104:107], v[198:201], v[80:83]
	v_mfma_f32_16x16x32_bf16 v[84:87], v[112:115], v[198:201], v[84:87]
	v_mfma_f32_16x16x32_bf16 v[88:91], v[104:107], v[206:209], v[88:91]
	v_mfma_f32_16x16x32_bf16 v[92:95], v[112:115], v[206:209], v[92:95]
	v_mfma_f32_16x16x32_bf16 v[64:67], v[108:111], v[186:189], v[64:67]
	v_mfma_f32_16x16x32_bf16 v[68:71], v[116:119], v[186:189], v[68:71]
	v_mfma_f32_16x16x32_bf16 v[72:75], v[108:111], v[194:197], v[72:75]
	v_mfma_f32_16x16x32_bf16 v[76:79], v[116:119], v[194:197], v[76:79]
	v_mfma_f32_16x16x32_bf16 v[80:83], v[108:111], v[202:205], v[80:83]
	v_mfma_f32_16x16x32_bf16 v[84:87], v[116:119], v[202:205], v[84:87]
	v_mfma_f32_16x16x32_bf16 v[88:91], v[108:111], v[210:213], v[88:91]
	v_mfma_f32_16x16x32_bf16 v[92:95], v[116:119], v[210:213], v[92:95]
	s_setprio 0
	s_setprio 1
	v_mfma_f32_16x16x32_bf16 v[32:35], v[174:177], v[182:185], v[32:35]
	v_mfma_f32_16x16x32_bf16 v[96:99], v[120:123], v[182:185], v[96:99]
	v_mfma_f32_16x16x32_bf16 v[182:185], v[178:181], v[186:189], v[32:35]
	v_mfma_f32_16x16x32_bf16 v[32:35], v[120:123], v[190:193], v[36:39]
	v_mfma_f32_16x16x32_bf16 v[214:217], v[124:127], v[186:189], v[96:99]
	v_mfma_f32_16x16x32_bf16 v[186:189], v[124:127], v[194:197], v[32:35]
	v_mfma_f32_16x16x32_bf16 v[32:35], v[174:177], v[190:193], v[40:43]
	v_mfma_f32_16x16x32_bf16 v[40:43], v[178:181], v[194:197], v[32:35]
	v_mfma_f32_16x16x32_bf16 v[32:35], v[120:123], v[198:201], v[44:47]
	v_mfma_f32_16x16x32_bf16 v[44:47], v[124:127], v[202:205], v[32:35]
	v_mfma_f32_16x16x32_bf16 v[32:35], v[174:177], v[198:201], v[48:51]
	v_mfma_f32_16x16x32_bf16 v[48:51], v[178:181], v[202:205], v[32:35]
	v_mfma_f32_16x16x32_bf16 v[32:35], v[120:123], v[206:209], v[52:55]
	v_mfma_f32_16x16x32_bf16 v[52:55], v[124:127], v[210:213], v[32:35]
	v_mfma_f32_16x16x32_bf16 v[32:35], v[174:177], v[206:209], v[56:59]
	v_mfma_f32_16x16x32_bf16 v[56:59], v[178:181], v[210:213], v[32:35]
	s_setprio 0
	s_barrier
	s_mov_b32 m0, s58
	v_lshl_add_u64 v[250:251], s[40:41], 0, v[130:131]
	s_add_u32 s36, s40, 0x10000
	s_nop 1
	ds_read_b128 v[32:35], v147 offset:16384
	ds_read_b128 v[36:39], v147 offset:17408
	ds_read_b128 v[96:99], v147 offset:18432
	ds_read_b128 v[190:193], v147 offset:19456
	ds_read_b128 v[194:197], v147 offset:20480
	ds_read_b128 v[198:201], v147 offset:21504
	ds_read_b128 v[202:205], v147 offset:22528
	ds_read_b128 v[206:209], v147 offset:23552
	global_load_lds_dwordx4 v[250:251], off
	v_lshl_add_u64 v[252:253], s[40:41], 0, v[134:135]
	s_mov_b32 m0, s59
	s_addc_u32 s37, s41, 0
	global_load_lds_dwordx4 v[252:253], off
	s_mov_b32 m0, s60
	v_lshl_add_u64 v[138:139], s[42:43], 0, v[128:129]
	global_load_lds_dwordx4 v130, s[36:37]
	s_mov_b32 m0, s61
	v_lshl_add_u64 v[140:141], s[42:43], 0, v[132:133]
	global_load_lds_dwordx4 v134, s[36:37]
	s_mov_b32 m0, s49
	s_nop 0
	global_load_lds_dwordx4 v[138:139], off
	s_mov_b32 m0, s50
	s_nop 0
	global_load_lds_dwordx4 v[140:141], off
	s_waitcnt vmcnt(8)
	s_waitcnt lgkmcnt(0)
	s_barrier
	s_setprio 1
	s_waitcnt lgkmcnt(0)
	v_mfma_f32_16x16x32_bf16 v[0:3], v[104:107], v[202:205], v[0:3]
	v_mfma_f32_16x16x32_bf16 v[4:7], v[112:115], v[202:205], v[4:7]
	v_mfma_f32_16x16x32_bf16 v[150:153], v[104:107], v[32:35], v[150:153]
	v_mfma_f32_16x16x32_bf16 v[154:157], v[112:115], v[32:35], v[154:157]
	v_mfma_f32_16x16x32_bf16 v[158:161], v[104:107], v[96:99], v[158:161]
	v_mfma_f32_16x16x32_bf16 v[162:165], v[112:115], v[96:99], v[162:165]
	v_mfma_f32_16x16x32_bf16 v[166:169], v[104:107], v[194:197], v[166:169]
	v_mfma_f32_16x16x32_bf16 v[170:173], v[112:115], v[194:197], v[170:173]
	v_mfma_f32_16x16x32_bf16 v[0:3], v[108:111], v[206:209], v[0:3]
	v_mfma_f32_16x16x32_bf16 v[4:7], v[116:119], v[206:209], v[4:7]
	v_mfma_f32_16x16x32_bf16 v[150:153], v[108:111], v[36:39], v[150:153]
	v_mfma_f32_16x16x32_bf16 v[154:157], v[116:119], v[36:39], v[154:157]
	v_mfma_f32_16x16x32_bf16 v[158:161], v[108:111], v[190:193], v[158:161]
	v_mfma_f32_16x16x32_bf16 v[162:165], v[116:119], v[190:193], v[162:165]
	v_mfma_f32_16x16x32_bf16 v[166:169], v[108:111], v[198:201], v[166:169]
	v_mfma_f32_16x16x32_bf16 v[170:173], v[116:119], v[198:201], v[170:173]
	s_setprio 0
	s_setprio 1
	v_mfma_f32_16x16x32_bf16 v[8:11], v[120:123], v[32:35], v[8:11]
	v_mfma_f32_16x16x32_bf16 v[12:15], v[174:177], v[32:35], v[12:15]
	v_mfma_f32_16x16x32_bf16 v[24:27], v[120:123], v[96:99], v[24:27]
	v_mfma_f32_16x16x32_bf16 v[28:31], v[174:177], v[96:99], v[28:31]
	v_mfma_f32_16x16x32_bf16 v[32:35], v[120:123], v[194:197], v[60:63]
	v_mfma_f32_16x16x32_bf16 v[24:27], v[124:127], v[190:193], v[24:27]
	v_mfma_f32_16x16x32_bf16 v[28:31], v[178:181], v[190:193], v[28:31]
	v_mfma_f32_16x16x32_bf16 v[190:193], v[124:127], v[198:201], v[32:35]
	v_mfma_f32_16x16x32_bf16 v[32:35], v[174:177], v[194:197], v[100:103]
	v_mfma_f32_16x16x32_bf16 v[16:19], v[120:123], v[202:205], v[16:19]
	v_mfma_f32_16x16x32_bf16 v[8:11], v[124:127], v[36:39], v[8:11]
	v_mfma_f32_16x16x32_bf16 v[12:15], v[178:181], v[36:39], v[12:15]
	v_mfma_f32_16x16x32_bf16 v[194:197], v[178:181], v[198:201], v[32:35]
	v_mfma_f32_16x16x32_bf16 v[198:201], v[124:127], v[206:209], v[16:19]
	v_mfma_f32_16x16x32_bf16 v[16:19], v[174:177], v[202:205], v[20:23]
	v_mfma_f32_16x16x32_bf16 v[174:177], v[178:181], v[206:209], v[16:19]
	s_setprio 0
	s_barrier
	ds_read_b128 v[60:63], v148
	ds_read_b128 v[178:181], v148 offset:1024
	ds_read_b128 v[202:205], v148 offset:2048
	ds_read_b128 v[206:209], v148 offset:3072
	ds_read_b128 v[210:213], v149
	ds_read_b128 v[218:221], v149 offset:1024
	ds_read_b128 v[222:225], v149 offset:2048
	ds_read_b128 v[226:229], v149 offset:3072
	s_add_u32 s36, s42, 0x10000
	s_addc_u32 s37, s43, 0
	s_mov_b32 m0, s51
	ds_read_b128 v[16:19], v147 offset:32768
	ds_read_b128 v[20:23], v147 offset:33792
	ds_read_b128 v[108:111], v147 offset:34816
	ds_read_b128 v[230:233], v147 offset:35840
	ds_read_b128 v[234:237], v147 offset:36864
	ds_read_b128 v[238:241], v147 offset:37888
	ds_read_b128 v[242:245], v147 offset:38912
	ds_read_b128 v[246:249], v147 offset:39936
	global_load_lds_dwordx4 v128, s[36:37]
	s_mov_b32 m0, s52
	s_nop 0
	global_load_lds_dwordx4 v132, s[36:37]
	s_waitcnt vmcnt(8)
	s_waitcnt lgkmcnt(0)
	s_barrier
	s_setprio 1
	s_waitcnt lgkmcnt(0)
	v_mfma_f32_16x16x32_bf16 v[32:35], v[60:63], v[16:19], v[64:67]
	v_mfma_f32_16x16x32_bf16 v[120:123], v[178:181], v[20:23], v[32:35]
	v_mfma_f32_16x16x32_bf16 v[32:35], v[202:205], v[16:19], v[68:71]
	v_mfma_f32_16x16x32_bf16 v[124:127], v[206:209], v[20:23], v[32:35]
	v_mfma_f32_16x16x32_bf16 v[32:35], v[60:63], v[108:111], v[72:75]
	v_mfma_f32_16x16x32_bf16 v[96:99], v[178:181], v[230:233], v[32:35]
	v_mfma_f32_16x16x32_bf16 v[32:35], v[202:205], v[108:111], v[76:79]
	v_mfma_f32_16x16x32_bf16 v[100:103], v[206:209], v[230:233], v[32:35]
	v_mfma_f32_16x16x32_bf16 v[32:35], v[60:63], v[234:237], v[80:83]
	v_mfma_f32_16x16x32_bf16 v[64:67], v[178:181], v[238:241], v[32:35]
	v_mfma_f32_16x16x32_bf16 v[32:35], v[202:205], v[234:237], v[84:87]
	v_mfma_f32_16x16x32_bf16 v[68:71], v[206:209], v[238:241], v[32:35]
	v_mfma_f32_16x16x32_bf16 v[32:35], v[60:63], v[242:245], v[88:91]
	v_mfma_f32_16x16x32_bf16 v[36:39], v[202:205], v[242:245], v[92:95]
	v_mfma_f32_16x16x32_bf16 v[32:35], v[178:181], v[246:249], v[32:35]
	v_mfma_f32_16x16x32_bf16 v[36:39], v[206:209], v[246:249], v[36:39]
	s_setprio 0
	s_setprio 1
	v_mfma_f32_16x16x32_bf16 v[72:75], v[210:213], v[16:19], v[214:217]
	v_mfma_f32_16x16x32_bf16 v[16:19], v[222:225], v[16:19], v[182:185]
	v_mfma_f32_16x16x32_bf16 v[116:119], v[226:229], v[20:23], v[16:19]
	v_mfma_f32_16x16x32_bf16 v[16:19], v[210:213], v[108:111], v[186:189]
	v_mfma_f32_16x16x32_bf16 v[104:107], v[218:221], v[230:233], v[16:19]
	v_mfma_f32_16x16x32_bf16 v[16:19], v[222:225], v[108:111], v[40:43]
	v_mfma_f32_16x16x32_bf16 v[108:111], v[226:229], v[230:233], v[16:19]
	v_mfma_f32_16x16x32_bf16 v[16:19], v[210:213], v[234:237], v[44:47]
	v_mfma_f32_16x16x32_bf16 v[112:115], v[218:221], v[20:23], v[72:75]
	v_mfma_f32_16x16x32_bf16 v[72:75], v[218:221], v[238:241], v[16:19]
	v_mfma_f32_16x16x32_bf16 v[16:19], v[222:225], v[234:237], v[48:51]
	v_mfma_f32_16x16x32_bf16 v[76:79], v[226:229], v[238:241], v[16:19]
	v_mfma_f32_16x16x32_bf16 v[16:19], v[210:213], v[242:245], v[52:55]
	v_mfma_f32_16x16x32_bf16 v[40:43], v[218:221], v[246:249], v[16:19]
	v_mfma_f32_16x16x32_bf16 v[16:19], v[222:225], v[242:245], v[56:59]
	v_mfma_f32_16x16x32_bf16 v[44:47], v[226:229], v[246:249], v[16:19]
	s_setprio 0
	s_barrier
	s_mov_b32 m0, s63
	s_nop 3
	v_lshl_add_u64 v[16:17], v[250:251], 0, s[12:13]
	s_add_u32 s36, s40, 0x10080
	ds_read_b128 v[56:59], v147 offset:49152
	ds_read_b128 v[92:95], v147 offset:50176
	ds_read_b128 v[182:185], v147 offset:51200
	ds_read_b128 v[186:189], v147 offset:52224
	ds_read_b128 v[214:217], v147 offset:53248
	ds_read_b128 v[230:233], v147 offset:54272
	ds_read_b128 v[234:237], v147 offset:55296
	ds_read_b128 v[238:241], v147 offset:56320
	global_load_lds_dwordx4 v[16:17], off
	v_lshl_add_u64 v[16:17], v[252:253], 0, s[12:13]
	s_mov_b32 m0, s23
	s_addc_u32 s37, s41, 0
	global_load_lds_dwordx4 v[16:17], off
	s_mov_b32 m0, s25
	s_nop 0
	global_load_lds_dwordx4 v130, s[36:37]
	s_mov_b32 m0, s38
	s_nop 0
	global_load_lds_dwordx4 v134, s[36:37]
	v_lshl_add_u64 v[16:17], v[138:139], 0, s[12:13]
	s_mov_b32 m0, s53
	s_nop 0
	global_load_lds_dwordx4 v[16:17], off
	v_lshl_add_u64 v[16:17], v[140:141], 0, s[12:13]
	s_mov_b32 m0, s54
	s_nop 0
	global_load_lds_dwordx4 v[16:17], off
	s_waitcnt vmcnt(8)
	s_waitcnt lgkmcnt(0)
	s_barrier
	s_setprio 1
	s_waitcnt lgkmcnt(0)
	v_mfma_f32_16x16x32_bf16 v[16:19], v[60:63], v[56:59], v[150:153]
	v_mfma_f32_16x16x32_bf16 v[80:83], v[178:181], v[92:95], v[16:19]
	v_mfma_f32_16x16x32_bf16 v[16:19], v[202:205], v[56:59], v[154:157]
	v_mfma_f32_16x16x32_bf16 v[84:87], v[206:209], v[92:95], v[16:19]
	v_mfma_f32_16x16x32_bf16 v[16:19], v[60:63], v[182:185], v[158:161]
	v_mfma_f32_16x16x32_bf16 v[48:51], v[178:181], v[186:189], v[16:19]
	v_mfma_f32_16x16x32_bf16 v[16:19], v[202:205], v[182:185], v[162:165]
	v_mfma_f32_16x16x32_bf16 v[52:55], v[206:209], v[186:189], v[16:19]
	v_mfma_f32_16x16x32_bf16 v[16:19], v[60:63], v[214:217], v[166:169]
	v_mfma_f32_16x16x32_bf16 v[20:23], v[202:205], v[214:217], v[170:173]
	v_mfma_f32_16x16x32_bf16 v[0:3], v[60:63], v[234:237], v[0:3]
	v_mfma_f32_16x16x32_bf16 v[4:7], v[202:205], v[234:237], v[4:7]
	v_mfma_f32_16x16x32_bf16 v[16:19], v[178:181], v[230:233], v[16:19]
	v_mfma_f32_16x16x32_bf16 v[20:23], v[206:209], v[230:233], v[20:23]
	v_mfma_f32_16x16x32_bf16 v[0:3], v[178:181], v[238:241], v[0:3]
	v_mfma_f32_16x16x32_bf16 v[4:7], v[206:209], v[238:241], v[4:7]
	s_setprio 0
	s_setprio 1
	v_mfma_f32_16x16x32_bf16 v[8:11], v[210:213], v[56:59], v[8:11]
	v_mfma_f32_16x16x32_bf16 v[88:91], v[218:221], v[92:95], v[8:11]
	v_mfma_f32_16x16x32_bf16 v[8:11], v[222:225], v[56:59], v[12:15]
	v_mfma_f32_16x16x32_bf16 v[92:95], v[226:229], v[92:95], v[8:11]
	v_mfma_f32_16x16x32_bf16 v[8:11], v[210:213], v[182:185], v[24:27]
	v_mfma_f32_16x16x32_bf16 v[56:59], v[218:221], v[186:189], v[8:11]
	v_mfma_f32_16x16x32_bf16 v[8:11], v[222:225], v[182:185], v[28:31]
	v_mfma_f32_16x16x32_bf16 v[60:63], v[226:229], v[186:189], v[8:11]
	v_mfma_f32_16x16x32_bf16 v[8:11], v[210:213], v[214:217], v[190:193]
	v_mfma_f32_16x16x32_bf16 v[24:27], v[218:221], v[230:233], v[8:11]
	v_mfma_f32_16x16x32_bf16 v[8:11], v[222:225], v[214:217], v[194:197]
	v_mfma_f32_16x16x32_bf16 v[28:31], v[226:229], v[230:233], v[8:11]
	v_mfma_f32_16x16x32_bf16 v[8:11], v[210:213], v[234:237], v[198:201]
	v_mfma_f32_16x16x32_bf16 v[12:15], v[222:225], v[234:237], v[174:177]
	v_mfma_f32_16x16x32_bf16 v[8:11], v[218:221], v[238:241], v[8:11]
	v_mfma_f32_16x16x32_bf16 v[12:15], v[226:229], v[238:241], v[12:15]
	s_setprio 0
	s_barrier
	s_andn2_b64 vcc, exec, s[14:15]
	s_cbranch_vccnz .LBB0_997
	s_barrier

.LBB0_1008:
	s_add_u32 s54, s76, 0x2c00800
	s_addc_u32 s55, s77, 0
	s_add_u32 s56, s76, 0x2100800
	s_addc_u32 s57, s77, 0
	s_lshl_b32 s14, s14, 5
	s_and_b32 s17, s14, 0x60
	s_mov_b64 s[14:15], 0x80
	s_add_i32 m0, s25, 0x18000
	v_lshl_add_u64 v[6:7], v[6:7], 0, s[14:15]
	s_waitcnt vmcnt(2)
	s_barrier
	global_load_lds_dwordx4 v[6:7], off
	v_lshl_add_u64 v[4:5], v[4:5], 0, s[14:15]
	s_add_i32 m0, s25, 0x1a000
	s_add_i32 s58, s25, 0x8000
	s_lshl_b32 s16, s1, 13
	s_lshl_b32 s18, s17, 7
	global_load_lds_dwordx4 v[4:5], off
	v_lshl_add_u64 v[0:1], v[0:1], 0, s[14:15]
	s_mov_b32 m0, s58
	s_add_i32 s59, s25, 0xa000
	global_load_lds_dwordx4 v[0:1], off
	v_lshl_add_u64 v[0:1], v[2:3], 0, s[14:15]
	s_add_u32 s14, s26, 0x40080
	s_mov_b32 m0, s59
	s_addc_u32 s15, s27, 0
	global_load_lds_dwordx4 v[0:1], off
	s_add_i32 m0, s25, 0x1c000
	s_nop 0
	global_load_lds_dwordx4 v186, s[14:15]
	s_add_i32 m0, s25, 0x1e000
	v_and_b32_e32 v2, 15, v8
	global_load_lds_dwordx4 v190, s[14:15]
	v_bfe_u32 v1, v8, 4, 2
	v_lshlrev_b32_e32 v0, 4, v1
	v_lshlrev_b32_e32 v3, 2, v8
	v_lshl_or_b32 v193, s1, 6, v2
	v_lshl_or_b32 v2, v2, 6, v0
	v_and_b32_e32 v3, 32, v3
	v_lshl_or_b32 v192, v1, 3, s17
	v_mov_b32_e32 v1, v187
	v_bitop3_b32 v4, v2, s16, v3 bitop3:0xde
	v_lshl_add_u64 v[0:1], s[76:77], 0, v[0:1]
	s_mov_b64 s[16:17], 0x2a00000
	v_lshl_add_u64 v[194:195], v[0:1], 0, s[16:17]
	v_lshlrev_b32_e32 v0, 14, v9
	v_and_b32_e32 v0, 0xffff8000, v0
	v_lshl_add_u32 v0, v10, 11, v0
	v_and_b32_e32 v1, 1, v9
	v_lshl_or_b32 v0, v1, 6, v0
	s_sext_i32_i8 s64, s0
	s_mov_b64 s[0:1], 0x40080
	v_lshl_add_u32 v0, v11, 1, v0
	v_mov_b32_e32 v1, v187
	v_lshl_add_u64 v[196:197], v[0:1], 0, s[0:1]
	v_lshlrev_b32_e32 v0, 14, v12
	v_and_b32_e32 v0, 0xffff8000, v0
	v_lshl_add_u32 v0, v13, 11, v0
	v_and_b32_e32 v1, 1, v12
	s_waitcnt vmcnt(6)
	v_lshl_or_b32 v0, v1, 6, v0
	s_cmpk_lt_u32 s10, 0x100
	v_lshl_add_u32 v0, v14, 1, v0
	v_mov_b32_e32 v1, v187
	v_bitop3_b32 v220, v2, s18, v3 bitop3:0xde
	s_cselect_b64 s[14:15], -1, 0
	s_ashr_i32 s60, s3, 31
	v_lshl_add_u64 v[198:199], v[0:1], 0, s[0:1]
	v_mov_b64_e32 v[200:201], 0x200
	v_mov_b64_e32 v[202:203], 0x1ff
	s_add_i32 s61, 0, 0x10000
	s_add_i32 s62, 0, 0x14000
	v_add_u32_e32 v221, 0, v4
	v_mov_b32_e32 v222, 0x358637bd
	s_mov_b32 s63, 0
	s_barrier
	s_branch .LBB0_1011

.LBB0_1018:
	v_add_u32_e32 v144, s61, v220
	v_add_u32_e32 v160, s62, v220
	ds_read_b128 v[132:135], v144
	ds_read_b128 v[136:139], v144 offset:1024
	ds_read_b128 v[140:143], v144 offset:2048
	ds_read_b128 v[144:147], v144 offset:3072
	ds_read_b128 v[148:151], v160
	ds_read_b128 v[152:155], v160 offset:1024
	ds_read_b128 v[156:159], v160 offset:2048
	ds_read_b128 v[160:163], v160 offset:3072
	s_add_u32 s10, s46, 0x100
	s_addc_u32 s76, s47, 0
	s_and_b64 s[46:47], exec, s[44:45]
	s_cselect_b32 s47, s19, s76
	s_cselect_b32 s46, s69, s10
	s_add_u32 s10, s73, 0x100
	s_addc_u32 s72, s72, 0
	s_and_b64 s[44:45], exec, s[44:45]
	s_cselect_b32 s45, s17, s72
	s_cselect_b32 s44, s70, s10
	v_lshl_add_u64 v[216:217], v[128:129], 0, s[38:39]
	s_add_i32 m0, s25, 0xc000
	ds_read_b128 v[164:167], v221
	ds_read_b128 v[168:171], v221 offset:1024
	ds_read_b128 v[172:175], v221 offset:2048
	ds_read_b128 v[176:179], v221 offset:3072
	ds_read_b128 v[180:183], v221 offset:4096
	ds_read_b128 v[204:207], v221 offset:5120
	ds_read_b128 v[208:211], v221 offset:6144
	ds_read_b128 v[212:215], v221 offset:7168
	global_load_lds_dwordx4 v[216:217], off
	v_lshl_add_u64 v[216:217], v[130:131], 0, s[38:39]
	s_add_i32 m0, s25, 0xe000
	s_nop 0
	global_load_lds_dwordx4 v[216:217], off
	s_waitcnt vmcnt(8)
	s_waitcnt lgkmcnt(0)
	s_barrier
	s_setprio 1
	s_waitcnt lgkmcnt(0)
	v_mfma_f32_16x16x32_bf16 v[124:127], v[132:135], v[164:167], v[124:127]
	v_mfma_f32_16x16x32_bf16 v[120:123], v[140:143], v[164:167], v[120:123]
	v_mfma_f32_16x16x32_bf16 v[108:111], v[132:135], v[172:175], v[108:111]
	v_mfma_f32_16x16x32_bf16 v[104:107], v[140:143], v[172:175], v[104:107]
	v_mfma_f32_16x16x32_bf16 v[92:95], v[132:135], v[180:183], v[92:95]
	v_mfma_f32_16x16x32_bf16 v[88:91], v[140:143], v[180:183], v[88:91]
	v_mfma_f32_16x16x32_bf16 v[76:79], v[132:135], v[208:211], v[76:79]
	v_mfma_f32_16x16x32_bf16 v[72:75], v[140:143], v[208:211], v[72:75]
	v_mfma_f32_16x16x32_bf16 v[124:127], v[136:139], v[168:171], v[124:127]
	v_mfma_f32_16x16x32_bf16 v[120:123], v[144:147], v[168:171], v[120:123]
	v_mfma_f32_16x16x32_bf16 v[108:111], v[136:139], v[176:179], v[108:111]
	v_mfma_f32_16x16x32_bf16 v[104:107], v[144:147], v[176:179], v[104:107]
	v_mfma_f32_16x16x32_bf16 v[92:95], v[136:139], v[204:207], v[92:95]
	v_mfma_f32_16x16x32_bf16 v[88:91], v[144:147], v[204:207], v[88:91]
	v_mfma_f32_16x16x32_bf16 v[76:79], v[136:139], v[212:215], v[76:79]
	v_mfma_f32_16x16x32_bf16 v[72:75], v[144:147], v[212:215], v[72:75]
	s_setprio 0
	s_setprio 1
	v_mfma_f32_16x16x32_bf16 v[116:119], v[148:151], v[164:167], v[116:119]
	v_mfma_f32_16x16x32_bf16 v[112:115], v[156:159], v[164:167], v[112:115]
	v_mfma_f32_16x16x32_bf16 v[100:103], v[148:151], v[172:175], v[100:103]
	v_mfma_f32_16x16x32_bf16 v[96:99], v[156:159], v[172:175], v[96:99]
	v_mfma_f32_16x16x32_bf16 v[84:87], v[148:151], v[180:183], v[84:87]
	v_mfma_f32_16x16x32_bf16 v[80:83], v[156:159], v[180:183], v[80:83]
	v_mfma_f32_16x16x32_bf16 v[68:71], v[148:151], v[208:211], v[68:71]
	v_mfma_f32_16x16x32_bf16 v[64:67], v[156:159], v[208:211], v[64:67]
	v_mfma_f32_16x16x32_bf16 v[116:119], v[152:155], v[168:171], v[116:119]
	v_mfma_f32_16x16x32_bf16 v[112:115], v[160:163], v[168:171], v[112:115]
	v_mfma_f32_16x16x32_bf16 v[100:103], v[152:155], v[176:179], v[100:103]
	v_mfma_f32_16x16x32_bf16 v[96:99], v[160:163], v[176:179], v[96:99]
	v_mfma_f32_16x16x32_bf16 v[84:87], v[152:155], v[204:207], v[84:87]
	v_mfma_f32_16x16x32_bf16 v[80:83], v[160:163], v[204:207], v[80:83]
	v_mfma_f32_16x16x32_bf16 v[68:71], v[152:155], v[212:215], v[68:71]
	v_mfma_f32_16x16x32_bf16 v[64:67], v[160:163], v[212:215], v[64:67]
	s_setprio 0
	s_barrier
	s_add_i32 s10, s61, s50
	s_mov_b32 m0, s10
	ds_read_b128 v[164:167], v221 offset:16384
	ds_read_b128 v[168:171], v221 offset:17408
	ds_read_b128 v[172:175], v221 offset:18432
	ds_read_b128 v[176:179], v221 offset:19456
	ds_read_b128 v[180:183], v221 offset:20480
	ds_read_b128 v[204:207], v221 offset:21504
	ds_read_b128 v[208:211], v221 offset:22528
	ds_read_b128 v[212:215], v221 offset:23552
	global_load_lds_dwordx4 v186, s[44:45]
	s_add_i32 m0, s10, 0x2000
	s_nop 0
	global_load_lds_dwordx4 v190, s[44:45]
	s_add_u32 s44, s44, 0x40000
	s_addc_u32 s45, s45, 0
	s_add_i32 s10, s62, s50
	s_mov_b32 m0, s10
	s_nop 0
	global_load_lds_dwordx4 v186, s[44:45]
	s_add_i32 m0, s10, 0x2000
	s_nop 0
	global_load_lds_dwordx4 v190, s[44:45]
	s_mov_b32 m0, s25
	s_nop 0
	global_load_lds_dwordx4 v184, s[46:47]
	s_mov_b32 m0, s51
	s_nop 0
	global_load_lds_dwordx4 v188, s[46:47]
	s_waitcnt vmcnt(8)
	s_waitcnt lgkmcnt(0)
	s_barrier
	s_setprio 1
	s_waitcnt lgkmcnt(0)
	v_mfma_f32_16x16x32_bf16 v[60:63], v[132:135], v[164:167], v[60:63]
	v_mfma_f32_16x16x32_bf16 v[56:59], v[140:143], v[164:167], v[56:59]
	v_mfma_f32_16x16x32_bf16 v[44:47], v[132:135], v[172:175], v[44:47]
	v_mfma_f32_16x16x32_bf16 v[40:43], v[140:143], v[172:175], v[40:43]
	v_mfma_f32_16x16x32_bf16 v[28:31], v[132:135], v[180:183], v[28:31]
	v_mfma_f32_16x16x32_bf16 v[24:27], v[140:143], v[180:183], v[24:27]
	v_mfma_f32_16x16x32_bf16 v[12:15], v[132:135], v[208:211], v[12:15]
	v_mfma_f32_16x16x32_bf16 v[8:11], v[140:143], v[208:211], v[8:11]
	v_mfma_f32_16x16x32_bf16 v[60:63], v[136:139], v[168:171], v[60:63]
	v_mfma_f32_16x16x32_bf16 v[56:59], v[144:147], v[168:171], v[56:59]
	v_mfma_f32_16x16x32_bf16 v[44:47], v[136:139], v[176:179], v[44:47]
	v_mfma_f32_16x16x32_bf16 v[40:43], v[144:147], v[176:179], v[40:43]
	v_mfma_f32_16x16x32_bf16 v[28:31], v[136:139], v[204:207], v[28:31]
	v_mfma_f32_16x16x32_bf16 v[24:27], v[144:147], v[204:207], v[24:27]
	v_mfma_f32_16x16x32_bf16 v[12:15], v[136:139], v[212:215], v[12:15]
	v_mfma_f32_16x16x32_bf16 v[8:11], v[144:147], v[212:215], v[8:11]
	s_setprio 0
	s_setprio 1
	v_mfma_f32_16x16x32_bf16 v[52:55], v[148:151], v[164:167], v[52:55]
	v_mfma_f32_16x16x32_bf16 v[48:51], v[156:159], v[164:167], v[48:51]
	v_mfma_f32_16x16x32_bf16 v[36:39], v[148:151], v[172:175], v[36:39]
	v_mfma_f32_16x16x32_bf16 v[32:35], v[156:159], v[172:175], v[32:35]
	v_mfma_f32_16x16x32_bf16 v[20:23], v[148:151], v[180:183], v[20:23]
	v_mfma_f32_16x16x32_bf16 v[16:19], v[156:159], v[180:183], v[16:19]
	v_mfma_f32_16x16x32_bf16 v[4:7], v[148:151], v[208:211], v[4:7]
	v_mfma_f32_16x16x32_bf16 v[0:3], v[156:159], v[208:211], v[0:3]
	v_mfma_f32_16x16x32_bf16 v[52:55], v[152:155], v[168:171], v[52:55]
	v_mfma_f32_16x16x32_bf16 v[48:51], v[160:163], v[168:171], v[48:51]
	v_mfma_f32_16x16x32_bf16 v[36:39], v[152:155], v[176:179], v[36:39]
	v_mfma_f32_16x16x32_bf16 v[32:35], v[160:163], v[176:179], v[32:35]
	v_mfma_f32_16x16x32_bf16 v[20:23], v[152:155], v[204:207], v[20:23]
	v_mfma_f32_16x16x32_bf16 v[16:19], v[160:163], v[204:207], v[16:19]
	v_mfma_f32_16x16x32_bf16 v[4:7], v[152:155], v[212:215], v[4:7]
	v_mfma_f32_16x16x32_bf16 v[0:3], v[160:163], v[212:215], v[0:3]
	s_setprio 0
	s_barrier
	s_add_i32 s10, 0, 0x18000
	s_add_i32 s72, 0, 0x1c000
	v_add_u32_e32 v144, s10, v220
	v_add_u32_e32 v160, s72, v220
	ds_read_b128 v[132:135], v144
	ds_read_b128 v[136:139], v144 offset:1024
	ds_read_b128 v[140:143], v144 offset:2048
	ds_read_b128 v[144:147], v144 offset:3072
	ds_read_b128 v[148:151], v160
	ds_read_b128 v[152:155], v160 offset:1024
	ds_read_b128 v[156:159], v160 offset:2048
	ds_read_b128 v[160:163], v160 offset:3072
	s_add_u32 s44, s46, 0x40000
	s_addc_u32 s45, s47, 0
	s_mov_b32 m0, s52
	ds_read_b128 v[164:167], v221 offset:32768
	ds_read_b128 v[168:171], v221 offset:33792
	ds_read_b128 v[172:175], v221 offset:34816
	ds_read_b128 v[176:179], v221 offset:35840
	ds_read_b128 v[180:183], v221 offset:36864
	ds_read_b128 v[204:207], v221 offset:37888
	ds_read_b128 v[208:211], v221 offset:38912
	ds_read_b128 v[212:215], v221 offset:39936
	global_load_lds_dwordx4 v184, s[44:45]
	s_mov_b32 m0, s53
	s_nop 0
	global_load_lds_dwordx4 v188, s[44:45]
	s_waitcnt vmcnt(8)
	s_waitcnt lgkmcnt(0)
	s_barrier
	s_setprio 1
	s_waitcnt lgkmcnt(0)
	v_mfma_f32_16x16x32_bf16 v[124:127], v[132:135], v[164:167], v[124:127]
	v_mfma_f32_16x16x32_bf16 v[120:123], v[140:143], v[164:167], v[120:123]
	v_mfma_f32_16x16x32_bf16 v[108:111], v[132:135], v[172:175], v[108:111]
	v_mfma_f32_16x16x32_bf16 v[104:107], v[140:143], v[172:175], v[104:107]
	v_mfma_f32_16x16x32_bf16 v[92:95], v[132:135], v[180:183], v[92:95]
	v_mfma_f32_16x16x32_bf16 v[88:91], v[140:143], v[180:183], v[88:91]
	v_mfma_f32_16x16x32_bf16 v[76:79], v[132:135], v[208:211], v[76:79]
	v_mfma_f32_16x16x32_bf16 v[72:75], v[140:143], v[208:211], v[72:75]
	v_mfma_f32_16x16x32_bf16 v[124:127], v[136:139], v[168:171], v[124:127]
	v_mfma_f32_16x16x32_bf16 v[120:123], v[144:147], v[168:171], v[120:123]
	v_mfma_f32_16x16x32_bf16 v[108:111], v[136:139], v[176:179], v[108:111]
	v_mfma_f32_16x16x32_bf16 v[104:107], v[144:147], v[176:179], v[104:107]
	v_mfma_f32_16x16x32_bf16 v[92:95], v[136:139], v[204:207], v[92:95]
	v_mfma_f32_16x16x32_bf16 v[88:91], v[144:147], v[204:207], v[88:91]
	v_mfma_f32_16x16x32_bf16 v[76:79], v[136:139], v[212:215], v[76:79]
	v_mfma_f32_16x16x32_bf16 v[72:75], v[144:147], v[212:215], v[72:75]
	s_setprio 0
	s_setprio 1
	v_mfma_f32_16x16x32_bf16 v[116:119], v[148:151], v[164:167], v[116:119]
	v_mfma_f32_16x16x32_bf16 v[112:115], v[156:159], v[164:167], v[112:115]
	v_mfma_f32_16x16x32_bf16 v[100:103], v[148:151], v[172:175], v[100:103]
	v_mfma_f32_16x16x32_bf16 v[96:99], v[156:159], v[172:175], v[96:99]
	v_mfma_f32_16x16x32_bf16 v[84:87], v[148:151], v[180:183], v[84:87]
	v_mfma_f32_16x16x32_bf16 v[80:83], v[156:159], v[180:183], v[80:83]
	v_mfma_f32_16x16x32_bf16 v[68:71], v[148:151], v[208:211], v[68:71]
	v_mfma_f32_16x16x32_bf16 v[64:67], v[156:159], v[208:211], v[64:67]
	v_mfma_f32_16x16x32_bf16 v[116:119], v[152:155], v[168:171], v[116:119]
	v_mfma_f32_16x16x32_bf16 v[112:115], v[160:163], v[168:171], v[112:115]
	v_mfma_f32_16x16x32_bf16 v[100:103], v[152:155], v[176:179], v[100:103]
	v_mfma_f32_16x16x32_bf16 v[96:99], v[160:163], v[176:179], v[96:99]
	v_mfma_f32_16x16x32_bf16 v[84:87], v[152:155], v[204:207], v[84:87]
	v_mfma_f32_16x16x32_bf16 v[80:83], v[160:163], v[204:207], v[80:83]
	v_mfma_f32_16x16x32_bf16 v[68:71], v[152:155], v[212:215], v[68:71]
	v_mfma_f32_16x16x32_bf16 v[64:67], v[160:163], v[212:215], v[64:67]
	s_setprio 0
	s_barrier
	s_add_i32 s10, s10, s50
	s_mov_b32 m0, s10
	ds_read_b128 v[164:167], v221 offset:49152
	ds_read_b128 v[168:171], v221 offset:50176
	ds_read_b128 v[172:175], v221 offset:51200
	ds_read_b128 v[176:179], v221 offset:52224
	ds_read_b128 v[180:183], v221 offset:53248
	ds_read_b128 v[204:207], v221 offset:54272
	ds_read_b128 v[208:211], v221 offset:55296
	ds_read_b128 v[212:215], v221 offset:56320
	global_load_lds_dwordx4 v186, s[42:43]
	s_add_i32 m0, s10, 0x2000
	s_nop 0
	global_load_lds_dwordx4 v190, s[42:43]
	s_add_u32 s42, s42, 0x40000
	s_addc_u32 s43, s43, 0
	s_add_i32 s10, s72, s50
	s_mov_b32 m0, s10
	s_nop 0
	global_load_lds_dwordx4 v186, s[42:43]
	s_add_i32 m0, s10, 0x2000
	s_nop 0
	global_load_lds_dwordx4 v190, s[42:43]
	s_mov_b32 m0, s58
	s_nop 0
	global_load_lds_dwordx4 v184, s[40:41]
	s_mov_b32 m0, s59
	s_nop 0
	global_load_lds_dwordx4 v188, s[40:41]
	s_waitcnt vmcnt(8)
	s_waitcnt lgkmcnt(0)
	s_barrier
	s_setprio 1
	s_waitcnt lgkmcnt(0)
	v_mfma_f32_16x16x32_bf16 v[60:63], v[132:135], v[164:167], v[60:63]
	v_mfma_f32_16x16x32_bf16 v[56:59], v[140:143], v[164:167], v[56:59]
	v_mfma_f32_16x16x32_bf16 v[44:47], v[132:135], v[172:175], v[44:47]
	v_mfma_f32_16x16x32_bf16 v[40:43], v[140:143], v[172:175], v[40:43]
	v_mfma_f32_16x16x32_bf16 v[28:31], v[132:135], v[180:183], v[28:31]
	v_mfma_f32_16x16x32_bf16 v[24:27], v[140:143], v[180:183], v[24:27]
	v_mfma_f32_16x16x32_bf16 v[12:15], v[132:135], v[208:211], v[12:15]
	v_mfma_f32_16x16x32_bf16 v[8:11], v[140:143], v[208:211], v[8:11]
	v_mfma_f32_16x16x32_bf16 v[60:63], v[136:139], v[168:171], v[60:63]
	v_mfma_f32_16x16x32_bf16 v[56:59], v[144:147], v[168:171], v[56:59]
	v_mfma_f32_16x16x32_bf16 v[44:47], v[136:139], v[176:179], v[44:47]
	v_mfma_f32_16x16x32_bf16 v[40:43], v[144:147], v[176:179], v[40:43]
	v_mfma_f32_16x16x32_bf16 v[28:31], v[136:139], v[204:207], v[28:31]
	v_mfma_f32_16x16x32_bf16 v[24:27], v[144:147], v[204:207], v[24:27]
	v_mfma_f32_16x16x32_bf16 v[12:15], v[136:139], v[212:215], v[12:15]
	v_mfma_f32_16x16x32_bf16 v[8:11], v[144:147], v[212:215], v[8:11]
	s_setprio 0
	s_setprio 1
	v_mfma_f32_16x16x32_bf16 v[52:55], v[148:151], v[164:167], v[52:55]
	v_mfma_f32_16x16x32_bf16 v[48:51], v[156:159], v[164:167], v[48:51]
	v_mfma_f32_16x16x32_bf16 v[36:39], v[148:151], v[172:175], v[36:39]
	v_mfma_f32_16x16x32_bf16 v[32:35], v[156:159], v[172:175], v[32:35]
	v_mfma_f32_16x16x32_bf16 v[20:23], v[148:151], v[180:183], v[20:23]
	v_mfma_f32_16x16x32_bf16 v[16:19], v[156:159], v[180:183], v[16:19]
	v_mfma_f32_16x16x32_bf16 v[4:7], v[148:151], v[208:211], v[4:7]
	v_mfma_f32_16x16x32_bf16 v[0:3], v[156:159], v[208:211], v[0:3]
	v_mfma_f32_16x16x32_bf16 v[52:55], v[152:155], v[168:171], v[52:55]
	v_mfma_f32_16x16x32_bf16 v[48:51], v[160:163], v[168:171], v[48:51]
	v_mfma_f32_16x16x32_bf16 v[36:39], v[152:155], v[176:179], v[36:39]
	v_mfma_f32_16x16x32_bf16 v[32:35], v[160:163], v[176:179], v[32:35]
	v_mfma_f32_16x16x32_bf16 v[20:23], v[152:155], v[204:207], v[20:23]
	v_mfma_f32_16x16x32_bf16 v[16:19], v[160:163], v[204:207], v[16:19]
	v_mfma_f32_16x16x32_bf16 v[4:7], v[152:155], v[212:215], v[4:7]
	v_mfma_f32_16x16x32_bf16 v[0:3], v[160:163], v[212:215], v[0:3]
	s_setprio 0
	s_barrier
	s_add_i32 s10, s71, 2
	s_add_u32 s38, s38, 0x100
	s_addc_u32 s39, s39, 0
	s_cmp_gt_u32 s71, 13
	s_mov_b32 s71, s10
	s_cbranch_scc1 .LBB0_1025
